# merge (gate x branch, RMW) epilogue rewritten as a 4-quarter software pipeline: loads always ahead of stores, later quarters load into consumed accumulators
# speedup vs baseline: 1.0040x; 1.0040x over previous
; __device__ __forceinline__ u32x4 pack8(const f32x4& a, const f32x4& b) { u32x4 w; w.x = pk2(a[0], a[1]); w.y = pk2(a[2], a[3]); w.z = pk2(b[0], b[1]); w.w = pk2(b[2], b[3]); return w; }
; __device__ __forceinline__ void unpack8(const u32x4& w, f32x4& a, f32x4& b) { a[0] = bflo(w.x); a[1] = bfhi(w.x); a[2] = bflo(w.y); a[3] = bfhi(w.y); b[0] = bflo(w.z); b[1] = bfhi(w.z); b[2] = bflo(w.w); b[3] = bfhi(w.w); }
;     __device__ __forceinline__ void operator()(const f32x4 (&acc)[2][2][4][2], const Unit& u, int wr, int wc, int fr, int fq) const {
;         const int br = u.kind / 3, part = u.kind % 3;
;         unsigned voff = (unsigned)((wr * 4 + wc) * 64 + fq * 16 + fr) * 16u; asm volatile("" : "+v"(voff));
;         unsigned char* const tmpb = ws + WS_SLAB + (size_t)(tslot >> 5) * SLAB + SL_TMP + (size_t)(tslot & 31) * 131072;
;         const int row0 = u.pm * BM + wr * 64 + fr, col0 = u.pn * BM + 32 * wc + 8 * fq;
;         if (part == 1) {
;     ...
;         } else {
;             bf16_t* const MRG = (bf16_t*)(ws + WS_SLAB + (size_t)(u.pm >> 4) * SLAB + SL_MRG); const int lrow0 = row0 & (SEQ - 1);
; #pragma unroll
;             for (int ai = 0; ai < 2; ++ai) {
;                 u32x4 gw[4][2], pw[4][2];
; #pragma unroll
;                 for (int m = 0; m < 4; ++m)
; #pragma unroll
;                     for (int bj = 0; bj < 2; ++bj) { gw[m][bj] = *(const u32x4*)(tmpb + ((ai * 4 + m) * 2 + bj) * 8192 + voff);
;                         if (br > 0) pw[m][bj] = *(const u32x4*)(MRG + (size_t)(lrow0 + ai * HALF + m * 16) * 1024 + col0 + 128 * bj); }
; #pragma unroll
;                 for (int m = 0; m < 4; ++m)
; #pragma unroll
;                     for (int bj = 0; bj < 2; ++bj) { f32x4 g0, g1; unpack8(gw[m][bj], g0, g1);
;                         f32x4 v0 = acc[ai][bj][m][0] * g0, v1 = acc[ai][bj][m][1] * g1;
;                         if (br > 0) { f32x4 p0, p1; unpack8(pw[m][bj], p0, p1); v0 += p0; v1 += p1; }
;                         *(u32x4*)(MRG + (size_t)(lrow0 + ai * HALF + m * 16) * 1024 + col0 + 128 * bj) = pack8(v0, v1); }
.LBB0_491:
	s_mul_i32 s10, s43, 0xab
	s_bfe_u32 s52, s10, 0x70009
	s_mul_i32 s10, s52, 3
	s_sub_i32 s10, s43, s10
	s_and_b32 s19, s10, 0xff
	s_cmp_lg_u32 s19, 0
	s_cselect_b64 s[34:35], -1, 0
	s_cmp_eq_u32 s19, 0
	s_cbranch_scc1 .LBB0_560
	v_mov_b32_e32 v192, v248
	v_lshl_add_u32 v210, s42, 8, v245
	v_lshl_or_b32 v208, s18, 8, v247
	s_cmp_lg_u32 s19, 1
	s_mov_b64 s[18:19], -1
	s_cbranch_scc0 .LBB0_558
	s_ashr_i32 s10, s42, 4
	s_mul_hi_i32 s11, s10, 0x1c00000
	s_mul_i32 s10, s10, 0x1c00000
	s_add_u32 s10, s71, s10
	s_addc_u32 s11, s72, s11
	v_lshlrev_b32_e32 v128, 1, v208
	v_mov_b32_e32 v129, v193
	v_lshlrev_b32_e32 v130, 11, v210
	s_cmp_gt_u32 s43, 2
	v_lshl_add_u64 v[128:129], s[10:11], 0, v[128:129]
	v_and_b32_e32 v130, 0x7e7800, v130
	v_mov_b32_e32 v131, v193
	s_cselect_b64 s[50:51], -1, 0
	v_lshl_add_u64 v[212:213], v[128:129], 0, v[130:131]
	v_lshl_add_u64 v[214:215], s[30:31], 0, v[192:193]
	v_cndmask_b32_e64 v128, 0, 1, s[50:51]
	s_nop 0
	v_cmp_ne_u32_e64 s[42:43], 1, v128
	s_and_b64 vcc, exec, s[50:51]
	s_cbranch_vccnz .Le2_rmw
	global_load_dwordx4 v[128:131], v[214:215], off
	s_mov_b64 s[10:11], 0x2000
	v_lshl_add_u64 v[224:225], v[214:215], 0, s[10:11]
	global_load_dwordx4 v[132:135], v[224:225], off
	s_mov_b64 s[10:11], 0x4000
	v_lshl_add_u64 v[224:225], v[214:215], 0, s[10:11]
	global_load_dwordx4 v[136:139], v[224:225], off
	s_mov_b64 s[10:11], 0x6000
	v_lshl_add_u64 v[224:225], v[214:215], 0, s[10:11]
	global_load_dwordx4 v[140:143], v[224:225], off
	s_mov_b64 s[10:11], 0x8000
	v_lshl_add_u64 v[224:225], v[214:215], 0, s[10:11]
	global_load_dwordx4 v[144:147], v[224:225], off
	s_mov_b64 s[10:11], 0xa000
	v_lshl_add_u64 v[224:225], v[214:215], 0, s[10:11]
	global_load_dwordx4 v[148:151], v[224:225], off
	s_mov_b64 s[10:11], 0xc000
	v_lshl_add_u64 v[224:225], v[214:215], 0, s[10:11]
	global_load_dwordx4 v[152:155], v[224:225], off
	s_mov_b64 s[10:11], 0xe000
	v_lshl_add_u64 v[224:225], v[214:215], 0, s[10:11]
	global_load_dwordx4 v[156:159], v[224:225], off
	s_waitcnt vmcnt(7)
	v_lshlrev_b32_e32 v216, 16, v128
	v_and_b32_e32 v217, 0xffff0000, v128
	v_lshlrev_b32_e32 v218, 16, v129
	v_and_b32_e32 v219, 0xffff0000, v129
	v_lshlrev_b32_e32 v220, 16, v130
	v_and_b32_e32 v221, 0xffff0000, v130
	v_lshlrev_b32_e32 v222, 16, v131
	v_and_b32_e32 v223, 0xffff0000, v131
	v_pk_mul_f32 v[124:125], v[124:125], v[216:217]
	v_pk_mul_f32 v[126:127], v[126:127], v[218:219]
	v_pk_mul_f32 v[120:121], v[120:121], v[220:221]
	v_pk_mul_f32 v[122:123], v[122:123], v[222:223]
	v_cvt_pk_bf16_f32 v128, v124, v125
	v_cvt_pk_bf16_f32 v129, v126, v127
	v_cvt_pk_bf16_f32 v130, v120, v121
	v_cvt_pk_bf16_f32 v131, v122, v123
	s_waitcnt vmcnt(6)
	v_lshlrev_b32_e32 v216, 16, v132
	v_and_b32_e32 v217, 0xffff0000, v132
	v_lshlrev_b32_e32 v218, 16, v133
	v_and_b32_e32 v219, 0xffff0000, v133
	v_lshlrev_b32_e32 v220, 16, v134
	v_and_b32_e32 v221, 0xffff0000, v134
	v_lshlrev_b32_e32 v222, 16, v135
	v_and_b32_e32 v223, 0xffff0000, v135
	v_pk_mul_f32 v[92:93], v[92:93], v[216:217]
	v_pk_mul_f32 v[94:95], v[94:95], v[218:219]
	v_pk_mul_f32 v[88:89], v[88:89], v[220:221]
	v_pk_mul_f32 v[90:91], v[90:91], v[222:223]
	v_cvt_pk_bf16_f32 v132, v92, v93
	v_cvt_pk_bf16_f32 v133, v94, v95
	v_cvt_pk_bf16_f32 v134, v88, v89
	v_cvt_pk_bf16_f32 v135, v90, v91
	s_waitcnt vmcnt(5)
	v_lshlrev_b32_e32 v216, 16, v136
	v_and_b32_e32 v217, 0xffff0000, v136
	v_lshlrev_b32_e32 v218, 16, v137
	v_and_b32_e32 v219, 0xffff0000, v137
	v_lshlrev_b32_e32 v220, 16, v138
	v_and_b32_e32 v221, 0xffff0000, v138
	v_lshlrev_b32_e32 v222, 16, v139
	v_and_b32_e32 v223, 0xffff0000, v139
	v_pk_mul_f32 v[116:117], v[116:117], v[216:217]
	v_pk_mul_f32 v[118:119], v[118:119], v[218:219]
	v_pk_mul_f32 v[112:113], v[112:113], v[220:221]
	v_pk_mul_f32 v[114:115], v[114:115], v[222:223]
	v_cvt_pk_bf16_f32 v136, v116, v117
	v_cvt_pk_bf16_f32 v137, v118, v119
	v_cvt_pk_bf16_f32 v138, v112, v113
	v_cvt_pk_bf16_f32 v139, v114, v115
	s_waitcnt vmcnt(4)
	v_lshlrev_b32_e32 v216, 16, v140
	v_and_b32_e32 v217, 0xffff0000, v140
	v_lshlrev_b32_e32 v218, 16, v141
	v_and_b32_e32 v219, 0xffff0000, v141
	v_lshlrev_b32_e32 v220, 16, v142
	v_and_b32_e32 v221, 0xffff0000, v142
	v_lshlrev_b32_e32 v222, 16, v143
	v_and_b32_e32 v223, 0xffff0000, v143
	v_pk_mul_f32 v[84:85], v[84:85], v[216:217]
	v_pk_mul_f32 v[86:87], v[86:87], v[218:219]
	v_pk_mul_f32 v[80:81], v[80:81], v[220:221]
	v_pk_mul_f32 v[82:83], v[82:83], v[222:223]
	v_cvt_pk_bf16_f32 v140, v84, v85
	v_cvt_pk_bf16_f32 v141, v86, v87
	v_cvt_pk_bf16_f32 v142, v80, v81
	v_cvt_pk_bf16_f32 v143, v82, v83
	s_mov_b64 s[10:11], 0x10000
	v_lshl_add_u64 v[224:225], v[214:215], 0, s[10:11]
	global_load_dwordx4 v[124:127], v[224:225], off
	s_mov_b64 s[10:11], 0x12000
	v_lshl_add_u64 v[224:225], v[214:215], 0, s[10:11]
	global_load_dwordx4 v[92:95], v[224:225], off
	s_mov_b64 s[10:11], 0x14000
	v_lshl_add_u64 v[224:225], v[214:215], 0, s[10:11]
	global_load_dwordx4 v[116:119], v[224:225], off
	s_mov_b64 s[10:11], 0x16000
	v_lshl_add_u64 v[224:225], v[214:215], 0, s[10:11]
	global_load_dwordx4 v[84:87], v[224:225], off
	global_store_dwordx4 v[212:213], v[128:131], off
	global_store_dwordx4 v[212:213], v[132:135], off offset:256
	s_mov_b64 s[10:11], 0x8000
	v_lshl_add_u64 v[224:225], v[212:213], 0, s[10:11]
	global_store_dwordx4 v[224:225], v[136:139], off
	s_mov_b64 s[10:11], 0x8000
	v_lshl_add_u64 v[224:225], v[212:213], 0, s[10:11]
	global_store_dwordx4 v[224:225], v[140:143], off offset:256
	s_waitcnt vmcnt(11)
; __device__ __forceinline__ u32x4 pack8(const f32x4& a, const f32x4& b) { u32x4 w; w.x = pk2(a[0], a[1]); w.y = pk2(a[2], a[3]); w.z = pk2(b[0], b[1]); w.w = pk2(b[2], b[3]); return w; }
; __device__ __forceinline__ void unpack8(const u32x4& w, f32x4& a, f32x4& b) { a[0] = bflo(w.x); a[1] = bfhi(w.x); a[2] = bflo(w.y); a[3] = bfhi(w.y); b[0] = bflo(w.z); b[1] = bfhi(w.z); b[2] = bflo(w.w); b[3] = bfhi(w.w); }
;     __device__ __forceinline__ void operator()(const f32x4 (&acc)[2][2][4][2], const Unit& u, int wr, int wc, int fr, int fq) const {
;     ...
;             for (int ai = 0; ai < 2; ++ai) {
;                 u32x4 gw[4][2], pw[4][2];
; #pragma unroll
;                 for (int m = 0; m < 4; ++m)
; #pragma unroll
;                     for (int bj = 0; bj < 2; ++bj) { gw[m][bj] = *(const u32x4*)(tmpb + ((ai * 4 + m) * 2 + bj) * 8192 + voff);
;                         if (br > 0) pw[m][bj] = *(const u32x4*)(MRG + (size_t)(lrow0 + ai * HALF + m * 16) * 1024 + col0 + 128 * bj); }
; #pragma unroll
;                 for (int m = 0; m < 4; ++m)
; #pragma unroll
;                     for (int bj = 0; bj < 2; ++bj) { f32x4 g0, g1; unpack8(gw[m][bj], g0, g1);
;                         f32x4 v0 = acc[ai][bj][m][0] * g0, v1 = acc[ai][bj][m][1] * g1;
;                         if (br > 0) { f32x4 p0, p1; unpack8(pw[m][bj], p0, p1); v0 += p0; v1 += p1; }
;                         *(u32x4*)(MRG + (size_t)(lrow0 + ai * HALF + m * 16) * 1024 + col0 + 128 * bj) = pack8(v0, v1); }
;                 asm volatile("" ::: "memory"); }
	v_lshlrev_b32_e32 v216, 16, v144
	v_and_b32_e32 v217, 0xffff0000, v144
	v_lshlrev_b32_e32 v218, 16, v145
	v_and_b32_e32 v219, 0xffff0000, v145
	v_lshlrev_b32_e32 v220, 16, v146
	v_and_b32_e32 v221, 0xffff0000, v146
	v_lshlrev_b32_e32 v222, 16, v147
	v_and_b32_e32 v223, 0xffff0000, v147
	v_pk_mul_f32 v[108:109], v[108:109], v[216:217]
	v_pk_mul_f32 v[110:111], v[110:111], v[218:219]
	v_pk_mul_f32 v[104:105], v[104:105], v[220:221]
	v_pk_mul_f32 v[106:107], v[106:107], v[222:223]
	v_cvt_pk_bf16_f32 v144, v108, v109
	v_cvt_pk_bf16_f32 v145, v110, v111
	v_cvt_pk_bf16_f32 v146, v104, v105
	v_cvt_pk_bf16_f32 v147, v106, v107
	s_waitcnt vmcnt(10)
	v_lshlrev_b32_e32 v216, 16, v148
	v_and_b32_e32 v217, 0xffff0000, v148
	v_lshlrev_b32_e32 v218, 16, v149
	v_and_b32_e32 v219, 0xffff0000, v149
	v_lshlrev_b32_e32 v220, 16, v150
	v_and_b32_e32 v221, 0xffff0000, v150
	v_lshlrev_b32_e32 v222, 16, v151
	v_and_b32_e32 v223, 0xffff0000, v151
	v_pk_mul_f32 v[76:77], v[76:77], v[216:217]
	v_pk_mul_f32 v[78:79], v[78:79], v[218:219]
	v_pk_mul_f32 v[72:73], v[72:73], v[220:221]
	v_pk_mul_f32 v[74:75], v[74:75], v[222:223]
	v_cvt_pk_bf16_f32 v148, v76, v77
	v_cvt_pk_bf16_f32 v149, v78, v79
	v_cvt_pk_bf16_f32 v150, v72, v73
	v_cvt_pk_bf16_f32 v151, v74, v75
	s_waitcnt vmcnt(9)
	v_lshlrev_b32_e32 v216, 16, v152
	v_and_b32_e32 v217, 0xffff0000, v152
	v_lshlrev_b32_e32 v218, 16, v153
	v_and_b32_e32 v219, 0xffff0000, v153
	v_lshlrev_b32_e32 v220, 16, v154
	v_and_b32_e32 v221, 0xffff0000, v154
	v_lshlrev_b32_e32 v222, 16, v155
	v_and_b32_e32 v223, 0xffff0000, v155
	v_pk_mul_f32 v[100:101], v[100:101], v[216:217]
	v_pk_mul_f32 v[102:103], v[102:103], v[218:219]
	v_pk_mul_f32 v[96:97], v[96:97], v[220:221]
	v_pk_mul_f32 v[98:99], v[98:99], v[222:223]
	v_cvt_pk_bf16_f32 v152, v100, v101
	v_cvt_pk_bf16_f32 v153, v102, v103
	v_cvt_pk_bf16_f32 v154, v96, v97
	v_cvt_pk_bf16_f32 v155, v98, v99
	s_waitcnt vmcnt(8)
	v_lshlrev_b32_e32 v216, 16, v156
	v_and_b32_e32 v217, 0xffff0000, v156
	v_lshlrev_b32_e32 v218, 16, v157
	v_and_b32_e32 v219, 0xffff0000, v157
	v_lshlrev_b32_e32 v220, 16, v158
	v_and_b32_e32 v221, 0xffff0000, v158
	v_lshlrev_b32_e32 v222, 16, v159
	v_and_b32_e32 v223, 0xffff0000, v159
	v_pk_mul_f32 v[68:69], v[68:69], v[216:217]
	v_pk_mul_f32 v[70:71], v[70:71], v[218:219]
	v_pk_mul_f32 v[64:65], v[64:65], v[220:221]
	v_pk_mul_f32 v[66:67], v[66:67], v[222:223]
	v_cvt_pk_bf16_f32 v156, v68, v69
	v_cvt_pk_bf16_f32 v157, v70, v71
	v_cvt_pk_bf16_f32 v158, v64, v65
	v_cvt_pk_bf16_f32 v159, v66, v67
	s_mov_b64 s[10:11], 0x18000
	v_lshl_add_u64 v[224:225], v[214:215], 0, s[10:11]
	global_load_dwordx4 v[108:111], v[224:225], off
	s_mov_b64 s[10:11], 0x1a000
	v_lshl_add_u64 v[224:225], v[214:215], 0, s[10:11]
	global_load_dwordx4 v[76:79], v[224:225], off
	s_mov_b64 s[10:11], 0x1c000
	v_lshl_add_u64 v[224:225], v[214:215], 0, s[10:11]
	global_load_dwordx4 v[100:103], v[224:225], off
	s_mov_b64 s[10:11], 0x1e000
	v_lshl_add_u64 v[224:225], v[214:215], 0, s[10:11]
	global_load_dwordx4 v[68:71], v[224:225], off
	s_mov_b64 s[10:11], 0x10000
	v_lshl_add_u64 v[224:225], v[212:213], 0, s[10:11]
	global_store_dwordx4 v[224:225], v[144:147], off
	s_mov_b64 s[10:11], 0x10000
	v_lshl_add_u64 v[224:225], v[212:213], 0, s[10:11]
	global_store_dwordx4 v[224:225], v[148:151], off offset:256
	s_mov_b64 s[10:11], 0x18000
	v_lshl_add_u64 v[224:225], v[212:213], 0, s[10:11]
	global_store_dwordx4 v[224:225], v[152:155], off
	s_mov_b64 s[10:11], 0x18000
	v_lshl_add_u64 v[224:225], v[212:213], 0, s[10:11]
	global_store_dwordx4 v[224:225], v[156:159], off offset:256
	s_waitcnt vmcnt(15)
	v_lshlrev_b32_e32 v216, 16, v124
	v_and_b32_e32 v217, 0xffff0000, v124
	v_lshlrev_b32_e32 v218, 16, v125
	v_and_b32_e32 v219, 0xffff0000, v125
	v_lshlrev_b32_e32 v220, 16, v126
	v_and_b32_e32 v221, 0xffff0000, v126
	v_lshlrev_b32_e32 v222, 16, v127
	v_and_b32_e32 v223, 0xffff0000, v127
	v_pk_mul_f32 v[60:61], v[60:61], v[216:217]
	v_pk_mul_f32 v[62:63], v[62:63], v[218:219]
	v_pk_mul_f32 v[56:57], v[56:57], v[220:221]
	v_pk_mul_f32 v[58:59], v[58:59], v[222:223]
	v_cvt_pk_bf16_f32 v124, v60, v61
	v_cvt_pk_bf16_f32 v125, v62, v63
	v_cvt_pk_bf16_f32 v126, v56, v57
	v_cvt_pk_bf16_f32 v127, v58, v59
	s_waitcnt vmcnt(14)
	v_lshlrev_b32_e32 v216, 16, v92
	v_and_b32_e32 v217, 0xffff0000, v92
	v_lshlrev_b32_e32 v218, 16, v93
	v_and_b32_e32 v219, 0xffff0000, v93
	v_lshlrev_b32_e32 v220, 16, v94
	v_and_b32_e32 v221, 0xffff0000, v94
	v_lshlrev_b32_e32 v222, 16, v95
	v_and_b32_e32 v223, 0xffff0000, v95
	v_pk_mul_f32 v[28:29], v[28:29], v[216:217]
	v_pk_mul_f32 v[30:31], v[30:31], v[218:219]
	v_pk_mul_f32 v[24:25], v[24:25], v[220:221]
	v_pk_mul_f32 v[26:27], v[26:27], v[222:223]
	v_cvt_pk_bf16_f32 v92, v28, v29
	v_cvt_pk_bf16_f32 v93, v30, v31
	v_cvt_pk_bf16_f32 v94, v24, v25
	v_cvt_pk_bf16_f32 v95, v26, v27
	s_waitcnt vmcnt(13)
	v_lshlrev_b32_e32 v216, 16, v116
	v_and_b32_e32 v217, 0xffff0000, v116
	v_lshlrev_b32_e32 v218, 16, v117
	v_and_b32_e32 v219, 0xffff0000, v117
	v_lshlrev_b32_e32 v220, 16, v118
	v_and_b32_e32 v221, 0xffff0000, v118
	v_lshlrev_b32_e32 v222, 16, v119
	v_and_b32_e32 v223, 0xffff0000, v119
	v_pk_mul_f32 v[52:53], v[52:53], v[216:217]
	v_pk_mul_f32 v[54:55], v[54:55], v[218:219]
	v_pk_mul_f32 v[48:49], v[48:49], v[220:221]
	v_pk_mul_f32 v[50:51], v[50:51], v[222:223]
	v_cvt_pk_bf16_f32 v116, v52, v53
	v_cvt_pk_bf16_f32 v117, v54, v55
	v_cvt_pk_bf16_f32 v118, v48, v49
	v_cvt_pk_bf16_f32 v119, v50, v51
	s_waitcnt vmcnt(12)
; __device__ __forceinline__ u32x4 pack8(const f32x4& a, const f32x4& b) { u32x4 w; w.x = pk2(a[0], a[1]); w.y = pk2(a[2], a[3]); w.z = pk2(b[0], b[1]); w.w = pk2(b[2], b[3]); return w; }
; __device__ __forceinline__ void unpack8(const u32x4& w, f32x4& a, f32x4& b) { a[0] = bflo(w.x); a[1] = bfhi(w.x); a[2] = bflo(w.y); a[3] = bfhi(w.y); b[0] = bflo(w.z); b[1] = bfhi(w.z); b[2] = bflo(w.w); b[3] = bfhi(w.w); }
;     __device__ __forceinline__ void operator()(const f32x4 (&acc)[2][2][4][2], const Unit& u, int wr, int wc, int fr, int fq) const {
;     ...
;             for (int ai = 0; ai < 2; ++ai) {
;                 u32x4 gw[4][2], pw[4][2];
; #pragma unroll
;                 for (int m = 0; m < 4; ++m)
; #pragma unroll
;                     for (int bj = 0; bj < 2; ++bj) { gw[m][bj] = *(const u32x4*)(tmpb + ((ai * 4 + m) * 2 + bj) * 8192 + voff);
;                         if (br > 0) pw[m][bj] = *(const u32x4*)(MRG + (size_t)(lrow0 + ai * HALF + m * 16) * 1024 + col0 + 128 * bj); }
; #pragma unroll
;                 for (int m = 0; m < 4; ++m)
; #pragma unroll
;                     for (int bj = 0; bj < 2; ++bj) { f32x4 g0, g1; unpack8(gw[m][bj], g0, g1);
;                         f32x4 v0 = acc[ai][bj][m][0] * g0, v1 = acc[ai][bj][m][1] * g1;
;                         if (br > 0) { f32x4 p0, p1; unpack8(pw[m][bj], p0, p1); v0 += p0; v1 += p1; }
;                         *(u32x4*)(MRG + (size_t)(lrow0 + ai * HALF + m * 16) * 1024 + col0 + 128 * bj) = pack8(v0, v1); }
;                 asm volatile("" ::: "memory"); }
	v_lshlrev_b32_e32 v216, 16, v84
	v_and_b32_e32 v217, 0xffff0000, v84
	v_lshlrev_b32_e32 v218, 16, v85
	v_and_b32_e32 v219, 0xffff0000, v85
	v_lshlrev_b32_e32 v220, 16, v86
	v_and_b32_e32 v221, 0xffff0000, v86
	v_lshlrev_b32_e32 v222, 16, v87
	v_and_b32_e32 v223, 0xffff0000, v87
	v_pk_mul_f32 v[20:21], v[20:21], v[216:217]
	v_pk_mul_f32 v[22:23], v[22:23], v[218:219]
	v_pk_mul_f32 v[16:17], v[16:17], v[220:221]
	v_pk_mul_f32 v[18:19], v[18:19], v[222:223]
	v_cvt_pk_bf16_f32 v84, v20, v21
	v_cvt_pk_bf16_f32 v85, v22, v23
	v_cvt_pk_bf16_f32 v86, v16, v17
	v_cvt_pk_bf16_f32 v87, v18, v19
	s_mov_b64 s[10:11], 0x40000
	v_lshl_add_u64 v[224:225], v[212:213], 0, s[10:11]
	global_store_dwordx4 v[224:225], v[124:127], off
	s_mov_b64 s[10:11], 0x40000
	v_lshl_add_u64 v[224:225], v[212:213], 0, s[10:11]
	global_store_dwordx4 v[224:225], v[92:95], off offset:256
	s_mov_b64 s[10:11], 0x48000
	v_lshl_add_u64 v[224:225], v[212:213], 0, s[10:11]
	global_store_dwordx4 v[224:225], v[116:119], off
	s_mov_b64 s[10:11], 0x48000
	v_lshl_add_u64 v[224:225], v[212:213], 0, s[10:11]
	global_store_dwordx4 v[224:225], v[84:87], off offset:256
	s_waitcnt vmcnt(11)
	v_lshlrev_b32_e32 v216, 16, v108
	v_and_b32_e32 v217, 0xffff0000, v108
	v_lshlrev_b32_e32 v218, 16, v109
	v_and_b32_e32 v219, 0xffff0000, v109
	v_lshlrev_b32_e32 v220, 16, v110
	v_and_b32_e32 v221, 0xffff0000, v110
	v_lshlrev_b32_e32 v222, 16, v111
	v_and_b32_e32 v223, 0xffff0000, v111
	v_pk_mul_f32 v[44:45], v[44:45], v[216:217]
	v_pk_mul_f32 v[46:47], v[46:47], v[218:219]
	v_pk_mul_f32 v[40:41], v[40:41], v[220:221]
	v_pk_mul_f32 v[42:43], v[42:43], v[222:223]
	v_cvt_pk_bf16_f32 v108, v44, v45
	v_cvt_pk_bf16_f32 v109, v46, v47
	v_cvt_pk_bf16_f32 v110, v40, v41
	v_cvt_pk_bf16_f32 v111, v42, v43
	s_waitcnt vmcnt(10)
	v_lshlrev_b32_e32 v216, 16, v76
	v_and_b32_e32 v217, 0xffff0000, v76
	v_lshlrev_b32_e32 v218, 16, v77
	v_and_b32_e32 v219, 0xffff0000, v77
	v_lshlrev_b32_e32 v220, 16, v78
	v_and_b32_e32 v221, 0xffff0000, v78
	v_lshlrev_b32_e32 v222, 16, v79
	v_and_b32_e32 v223, 0xffff0000, v79
	v_pk_mul_f32 v[12:13], v[12:13], v[216:217]
	v_pk_mul_f32 v[14:15], v[14:15], v[218:219]
	v_pk_mul_f32 v[8:9], v[8:9], v[220:221]
	v_pk_mul_f32 v[10:11], v[10:11], v[222:223]
	v_cvt_pk_bf16_f32 v76, v12, v13
	v_cvt_pk_bf16_f32 v77, v14, v15
	v_cvt_pk_bf16_f32 v78, v8, v9
	v_cvt_pk_bf16_f32 v79, v10, v11
	s_waitcnt vmcnt(9)
	v_lshlrev_b32_e32 v216, 16, v100
	v_and_b32_e32 v217, 0xffff0000, v100
	v_lshlrev_b32_e32 v218, 16, v101
	v_and_b32_e32 v219, 0xffff0000, v101
	v_lshlrev_b32_e32 v220, 16, v102
	v_and_b32_e32 v221, 0xffff0000, v102
	v_lshlrev_b32_e32 v222, 16, v103
	v_and_b32_e32 v223, 0xffff0000, v103
	v_pk_mul_f32 v[36:37], v[36:37], v[216:217]
	v_pk_mul_f32 v[38:39], v[38:39], v[218:219]
	v_pk_mul_f32 v[32:33], v[32:33], v[220:221]
	v_pk_mul_f32 v[34:35], v[34:35], v[222:223]
	v_cvt_pk_bf16_f32 v100, v36, v37
	v_cvt_pk_bf16_f32 v101, v38, v39
	v_cvt_pk_bf16_f32 v102, v32, v33
	v_cvt_pk_bf16_f32 v103, v34, v35
	s_waitcnt vmcnt(8)
	v_lshlrev_b32_e32 v216, 16, v68
	v_and_b32_e32 v217, 0xffff0000, v68
	v_lshlrev_b32_e32 v218, 16, v69
	v_and_b32_e32 v219, 0xffff0000, v69
	v_lshlrev_b32_e32 v220, 16, v70
	v_and_b32_e32 v221, 0xffff0000, v70
	v_lshlrev_b32_e32 v222, 16, v71
	v_and_b32_e32 v223, 0xffff0000, v71
	v_pk_mul_f32 v[4:5], v[4:5], v[216:217]
	v_pk_mul_f32 v[6:7], v[6:7], v[218:219]
	v_pk_mul_f32 v[0:1], v[0:1], v[220:221]
	v_pk_mul_f32 v[2:3], v[2:3], v[222:223]
	v_cvt_pk_bf16_f32 v68, v4, v5
	v_cvt_pk_bf16_f32 v69, v6, v7
	v_cvt_pk_bf16_f32 v70, v0, v1
	v_cvt_pk_bf16_f32 v71, v2, v3
	s_mov_b64 s[10:11], 0x50000
	v_lshl_add_u64 v[224:225], v[212:213], 0, s[10:11]
	global_store_dwordx4 v[224:225], v[108:111], off
	s_mov_b64 s[10:11], 0x50000
	v_lshl_add_u64 v[224:225], v[212:213], 0, s[10:11]
	global_store_dwordx4 v[224:225], v[76:79], off offset:256
	s_mov_b64 s[10:11], 0x58000
	v_lshl_add_u64 v[224:225], v[212:213], 0, s[10:11]
	global_store_dwordx4 v[224:225], v[100:103], off
	s_mov_b64 s[10:11], 0x58000
	v_lshl_add_u64 v[224:225], v[212:213], 0, s[10:11]
	global_store_dwordx4 v[224:225], v[68:71], off offset:256
	s_branch .Le2_done
.Le2_rmw:
	global_load_dwordx4 v[128:131], v[214:215], off
	global_load_dwordx4 v[132:135], v[212:213], off
	s_mov_b64 s[10:11], 0x2000
	v_lshl_add_u64 v[224:225], v[214:215], 0, s[10:11]
	global_load_dwordx4 v[136:139], v[224:225], off
	global_load_dwordx4 v[140:143], v[212:213], off offset:256
	s_mov_b64 s[10:11], 0x4000
	v_lshl_add_u64 v[224:225], v[214:215], 0, s[10:11]
	global_load_dwordx4 v[144:147], v[224:225], off
	s_mov_b64 s[10:11], 0x8000
	v_lshl_add_u64 v[232:233], v[212:213], 0, s[10:11]
	global_load_dwordx4 v[148:151], v[232:233], off
	s_mov_b64 s[10:11], 0x6000
	v_lshl_add_u64 v[224:225], v[214:215], 0, s[10:11]
	global_load_dwordx4 v[152:155], v[224:225], off
	s_mov_b64 s[10:11], 0x8000
	v_lshl_add_u64 v[232:233], v[212:213], 0, s[10:11]
	global_load_dwordx4 v[156:159], v[232:233], off offset:256
	s_mov_b64 s[10:11], 0x8000
	v_lshl_add_u64 v[224:225], v[214:215], 0, s[10:11]
	global_load_dwordx4 v[160:163], v[224:225], off
	s_mov_b64 s[10:11], 0x10000
	v_lshl_add_u64 v[232:233], v[212:213], 0, s[10:11]
	global_load_dwordx4 v[164:167], v[232:233], off
	s_mov_b64 s[10:11], 0xa000
	v_lshl_add_u64 v[224:225], v[214:215], 0, s[10:11]
	global_load_dwordx4 v[168:171], v[224:225], off
	s_mov_b64 s[10:11], 0x10000
	v_lshl_add_u64 v[232:233], v[212:213], 0, s[10:11]
	global_load_dwordx4 v[172:175], v[232:233], off offset:256
	s_mov_b64 s[10:11], 0xc000
	v_lshl_add_u64 v[224:225], v[214:215], 0, s[10:11]
	global_load_dwordx4 v[176:179], v[224:225], off
	s_mov_b64 s[10:11], 0x18000
	v_lshl_add_u64 v[232:233], v[212:213], 0, s[10:11]
	global_load_dwordx4 v[180:183], v[232:233], off
	s_mov_b64 s[10:11], 0xe000
	v_lshl_add_u64 v[224:225], v[214:215], 0, s[10:11]
	global_load_dwordx4 v[184:187], v[224:225], off
	s_mov_b64 s[10:11], 0x18000
	v_lshl_add_u64 v[232:233], v[212:213], 0, s[10:11]
	global_load_dwordx4 v[188:191], v[232:233], off offset:256
	s_waitcnt vmcnt(14)
; __device__ __forceinline__ u32x4 pack8(const f32x4& a, const f32x4& b) { u32x4 w; w.x = pk2(a[0], a[1]); w.y = pk2(a[2], a[3]); w.z = pk2(b[0], b[1]); w.w = pk2(b[2], b[3]); return w; }
; __device__ __forceinline__ void unpack8(const u32x4& w, f32x4& a, f32x4& b) { a[0] = bflo(w.x); a[1] = bfhi(w.x); a[2] = bflo(w.y); a[3] = bfhi(w.y); b[0] = bflo(w.z); b[1] = bfhi(w.z); b[2] = bflo(w.w); b[3] = bfhi(w.w); }
;     __device__ __forceinline__ void operator()(const f32x4 (&acc)[2][2][4][2], const Unit& u, int wr, int wc, int fr, int fq) const {
;     ...
;             for (int ai = 0; ai < 2; ++ai) {
;                 u32x4 gw[4][2], pw[4][2];
; #pragma unroll
;                 for (int m = 0; m < 4; ++m)
; #pragma unroll
;                     for (int bj = 0; bj < 2; ++bj) { gw[m][bj] = *(const u32x4*)(tmpb + ((ai * 4 + m) * 2 + bj) * 8192 + voff);
;                         if (br > 0) pw[m][bj] = *(const u32x4*)(MRG + (size_t)(lrow0 + ai * HALF + m * 16) * 1024 + col0 + 128 * bj); }
; #pragma unroll
;                 for (int m = 0; m < 4; ++m)
; #pragma unroll
;                     for (int bj = 0; bj < 2; ++bj) { f32x4 g0, g1; unpack8(gw[m][bj], g0, g1);
;                         f32x4 v0 = acc[ai][bj][m][0] * g0, v1 = acc[ai][bj][m][1] * g1;
;                         if (br > 0) { f32x4 p0, p1; unpack8(pw[m][bj], p0, p1); v0 += p0; v1 += p1; }
;                         *(u32x4*)(MRG + (size_t)(lrow0 + ai * HALF + m * 16) * 1024 + col0 + 128 * bj) = pack8(v0, v1); }
;                 asm volatile("" ::: "memory"); }
	v_lshlrev_b32_e32 v216, 16, v128
	v_and_b32_e32 v217, 0xffff0000, v128
	v_lshlrev_b32_e32 v218, 16, v129
	v_and_b32_e32 v219, 0xffff0000, v129
	v_lshlrev_b32_e32 v220, 16, v130
	v_and_b32_e32 v221, 0xffff0000, v130
	v_lshlrev_b32_e32 v222, 16, v131
	v_and_b32_e32 v223, 0xffff0000, v131
	v_pk_mul_f32 v[124:125], v[124:125], v[216:217]
	v_pk_mul_f32 v[126:127], v[126:127], v[218:219]
	v_pk_mul_f32 v[120:121], v[120:121], v[220:221]
	v_pk_mul_f32 v[122:123], v[122:123], v[222:223]
	v_lshlrev_b32_e32 v216, 16, v132
	v_and_b32_e32 v217, 0xffff0000, v132
	v_lshlrev_b32_e32 v218, 16, v133
	v_and_b32_e32 v219, 0xffff0000, v133
	v_lshlrev_b32_e32 v220, 16, v134
	v_and_b32_e32 v221, 0xffff0000, v134
	v_lshlrev_b32_e32 v222, 16, v135
	v_and_b32_e32 v223, 0xffff0000, v135
	v_pk_add_f32 v[124:125], v[124:125], v[216:217]
	v_pk_add_f32 v[126:127], v[126:127], v[218:219]
	v_pk_add_f32 v[120:121], v[120:121], v[220:221]
	v_pk_add_f32 v[122:123], v[122:123], v[222:223]
	v_cvt_pk_bf16_f32 v128, v124, v125
	v_cvt_pk_bf16_f32 v129, v126, v127
	v_cvt_pk_bf16_f32 v130, v120, v121
	v_cvt_pk_bf16_f32 v131, v122, v123
	s_waitcnt vmcnt(12)
	v_lshlrev_b32_e32 v216, 16, v136
	v_and_b32_e32 v217, 0xffff0000, v136
	v_lshlrev_b32_e32 v218, 16, v137
	v_and_b32_e32 v219, 0xffff0000, v137
	v_lshlrev_b32_e32 v220, 16, v138
	v_and_b32_e32 v221, 0xffff0000, v138
	v_lshlrev_b32_e32 v222, 16, v139
	v_and_b32_e32 v223, 0xffff0000, v139
	v_pk_mul_f32 v[92:93], v[92:93], v[216:217]
	v_pk_mul_f32 v[94:95], v[94:95], v[218:219]
	v_pk_mul_f32 v[88:89], v[88:89], v[220:221]
	v_pk_mul_f32 v[90:91], v[90:91], v[222:223]
	v_lshlrev_b32_e32 v216, 16, v140
	v_and_b32_e32 v217, 0xffff0000, v140
	v_lshlrev_b32_e32 v218, 16, v141
	v_and_b32_e32 v219, 0xffff0000, v141
	v_lshlrev_b32_e32 v220, 16, v142
	v_and_b32_e32 v221, 0xffff0000, v142
	v_lshlrev_b32_e32 v222, 16, v143
	v_and_b32_e32 v223, 0xffff0000, v143
	v_pk_add_f32 v[92:93], v[92:93], v[216:217]
	v_pk_add_f32 v[94:95], v[94:95], v[218:219]
	v_pk_add_f32 v[88:89], v[88:89], v[220:221]
	v_pk_add_f32 v[90:91], v[90:91], v[222:223]
	v_cvt_pk_bf16_f32 v136, v92, v93
	v_cvt_pk_bf16_f32 v137, v94, v95
	v_cvt_pk_bf16_f32 v138, v88, v89
	v_cvt_pk_bf16_f32 v139, v90, v91
	s_waitcnt vmcnt(10)
	v_lshlrev_b32_e32 v216, 16, v144
	v_and_b32_e32 v217, 0xffff0000, v144
	v_lshlrev_b32_e32 v218, 16, v145
	v_and_b32_e32 v219, 0xffff0000, v145
	v_lshlrev_b32_e32 v220, 16, v146
	v_and_b32_e32 v221, 0xffff0000, v146
	v_lshlrev_b32_e32 v222, 16, v147
	v_and_b32_e32 v223, 0xffff0000, v147
	v_pk_mul_f32 v[116:117], v[116:117], v[216:217]
	v_pk_mul_f32 v[118:119], v[118:119], v[218:219]
	v_pk_mul_f32 v[112:113], v[112:113], v[220:221]
	v_pk_mul_f32 v[114:115], v[114:115], v[222:223]
	v_lshlrev_b32_e32 v216, 16, v148
	v_and_b32_e32 v217, 0xffff0000, v148
	v_lshlrev_b32_e32 v218, 16, v149
	v_and_b32_e32 v219, 0xffff0000, v149
	v_lshlrev_b32_e32 v220, 16, v150
	v_and_b32_e32 v221, 0xffff0000, v150
	v_lshlrev_b32_e32 v222, 16, v151
	v_and_b32_e32 v223, 0xffff0000, v151
	v_pk_add_f32 v[116:117], v[116:117], v[216:217]
	v_pk_add_f32 v[118:119], v[118:119], v[218:219]
	v_pk_add_f32 v[112:113], v[112:113], v[220:221]
	v_pk_add_f32 v[114:115], v[114:115], v[222:223]
	v_cvt_pk_bf16_f32 v144, v116, v117
	v_cvt_pk_bf16_f32 v145, v118, v119
	v_cvt_pk_bf16_f32 v146, v112, v113
	v_cvt_pk_bf16_f32 v147, v114, v115
	s_waitcnt vmcnt(8)
	v_lshlrev_b32_e32 v216, 16, v152
	v_and_b32_e32 v217, 0xffff0000, v152
	v_lshlrev_b32_e32 v218, 16, v153
	v_and_b32_e32 v219, 0xffff0000, v153
	v_lshlrev_b32_e32 v220, 16, v154
	v_and_b32_e32 v221, 0xffff0000, v154
	v_lshlrev_b32_e32 v222, 16, v155
	v_and_b32_e32 v223, 0xffff0000, v155
	v_pk_mul_f32 v[84:85], v[84:85], v[216:217]
	v_pk_mul_f32 v[86:87], v[86:87], v[218:219]
	v_pk_mul_f32 v[80:81], v[80:81], v[220:221]
	v_pk_mul_f32 v[82:83], v[82:83], v[222:223]
	v_lshlrev_b32_e32 v216, 16, v156
	v_and_b32_e32 v217, 0xffff0000, v156
	v_lshlrev_b32_e32 v218, 16, v157
	v_and_b32_e32 v219, 0xffff0000, v157
	v_lshlrev_b32_e32 v220, 16, v158
	v_and_b32_e32 v221, 0xffff0000, v158
	v_lshlrev_b32_e32 v222, 16, v159
	v_and_b32_e32 v223, 0xffff0000, v159
	v_pk_add_f32 v[84:85], v[84:85], v[216:217]
	v_pk_add_f32 v[86:87], v[86:87], v[218:219]
	v_pk_add_f32 v[80:81], v[80:81], v[220:221]
	v_pk_add_f32 v[82:83], v[82:83], v[222:223]
	v_cvt_pk_bf16_f32 v152, v84, v85
	v_cvt_pk_bf16_f32 v153, v86, v87
	v_cvt_pk_bf16_f32 v154, v80, v81
	v_cvt_pk_bf16_f32 v155, v82, v83
	s_mov_b64 s[10:11], 0x10000
	v_lshl_add_u64 v[224:225], v[214:215], 0, s[10:11]
	global_load_dwordx4 v[124:127], v[224:225], off
	s_mov_b64 s[10:11], 0x40000
	v_lshl_add_u64 v[232:233], v[212:213], 0, s[10:11]
	global_load_dwordx4 v[120:123], v[232:233], off
	s_mov_b64 s[10:11], 0x12000
	v_lshl_add_u64 v[224:225], v[214:215], 0, s[10:11]
	global_load_dwordx4 v[92:95], v[224:225], off
	s_mov_b64 s[10:11], 0x40000
	v_lshl_add_u64 v[232:233], v[212:213], 0, s[10:11]
	global_load_dwordx4 v[88:91], v[232:233], off offset:256
	s_mov_b64 s[10:11], 0x14000
	v_lshl_add_u64 v[224:225], v[214:215], 0, s[10:11]
	global_load_dwordx4 v[116:119], v[224:225], off
	s_mov_b64 s[10:11], 0x48000
	v_lshl_add_u64 v[232:233], v[212:213], 0, s[10:11]
	global_load_dwordx4 v[112:115], v[232:233], off
	s_mov_b64 s[10:11], 0x16000
	v_lshl_add_u64 v[224:225], v[214:215], 0, s[10:11]
	global_load_dwordx4 v[84:87], v[224:225], off
	s_mov_b64 s[10:11], 0x48000
	v_lshl_add_u64 v[232:233], v[212:213], 0, s[10:11]
	global_load_dwordx4 v[80:83], v[232:233], off offset:256
	global_store_dwordx4 v[212:213], v[128:131], off
	global_store_dwordx4 v[212:213], v[136:139], off offset:256
	s_mov_b64 s[10:11], 0x8000
	v_lshl_add_u64 v[224:225], v[212:213], 0, s[10:11]
	global_store_dwordx4 v[224:225], v[144:147], off
	s_mov_b64 s[10:11], 0x8000
	v_lshl_add_u64 v[224:225], v[212:213], 0, s[10:11]
	global_store_dwordx4 v[224:225], v[152:155], off offset:256
	s_waitcnt vmcnt(18)
; __device__ __forceinline__ u32x4 pack8(const f32x4& a, const f32x4& b) { u32x4 w; w.x = pk2(a[0], a[1]); w.y = pk2(a[2], a[3]); w.z = pk2(b[0], b[1]); w.w = pk2(b[2], b[3]); return w; }
; __device__ __forceinline__ void unpack8(const u32x4& w, f32x4& a, f32x4& b) { a[0] = bflo(w.x); a[1] = bfhi(w.x); a[2] = bflo(w.y); a[3] = bfhi(w.y); b[0] = bflo(w.z); b[1] = bfhi(w.z); b[2] = bflo(w.w); b[3] = bfhi(w.w); }
;     __device__ __forceinline__ void operator()(const f32x4 (&acc)[2][2][4][2], const Unit& u, int wr, int wc, int fr, int fq) const {
;     ...
;             for (int ai = 0; ai < 2; ++ai) {
;                 u32x4 gw[4][2], pw[4][2];
; #pragma unroll
;                 for (int m = 0; m < 4; ++m)
; #pragma unroll
;                     for (int bj = 0; bj < 2; ++bj) { gw[m][bj] = *(const u32x4*)(tmpb + ((ai * 4 + m) * 2 + bj) * 8192 + voff);
;                         if (br > 0) pw[m][bj] = *(const u32x4*)(MRG + (size_t)(lrow0 + ai * HALF + m * 16) * 1024 + col0 + 128 * bj); }
; #pragma unroll
;                 for (int m = 0; m < 4; ++m)
; #pragma unroll
;                     for (int bj = 0; bj < 2; ++bj) { f32x4 g0, g1; unpack8(gw[m][bj], g0, g1);
;                         f32x4 v0 = acc[ai][bj][m][0] * g0, v1 = acc[ai][bj][m][1] * g1;
;                         if (br > 0) { f32x4 p0, p1; unpack8(pw[m][bj], p0, p1); v0 += p0; v1 += p1; }
;                         *(u32x4*)(MRG + (size_t)(lrow0 + ai * HALF + m * 16) * 1024 + col0 + 128 * bj) = pack8(v0, v1); }
;                 asm volatile("" ::: "memory"); }
	v_lshlrev_b32_e32 v216, 16, v160
	v_and_b32_e32 v217, 0xffff0000, v160
	v_lshlrev_b32_e32 v218, 16, v161
	v_and_b32_e32 v219, 0xffff0000, v161
	v_lshlrev_b32_e32 v220, 16, v162
	v_and_b32_e32 v221, 0xffff0000, v162
	v_lshlrev_b32_e32 v222, 16, v163
	v_and_b32_e32 v223, 0xffff0000, v163
	v_pk_mul_f32 v[108:109], v[108:109], v[216:217]
	v_pk_mul_f32 v[110:111], v[110:111], v[218:219]
	v_pk_mul_f32 v[104:105], v[104:105], v[220:221]
	v_pk_mul_f32 v[106:107], v[106:107], v[222:223]
	v_lshlrev_b32_e32 v216, 16, v164
	v_and_b32_e32 v217, 0xffff0000, v164
	v_lshlrev_b32_e32 v218, 16, v165
	v_and_b32_e32 v219, 0xffff0000, v165
	v_lshlrev_b32_e32 v220, 16, v166
	v_and_b32_e32 v221, 0xffff0000, v166
	v_lshlrev_b32_e32 v222, 16, v167
	v_and_b32_e32 v223, 0xffff0000, v167
	v_pk_add_f32 v[108:109], v[108:109], v[216:217]
	v_pk_add_f32 v[110:111], v[110:111], v[218:219]
	v_pk_add_f32 v[104:105], v[104:105], v[220:221]
	v_pk_add_f32 v[106:107], v[106:107], v[222:223]
	v_cvt_pk_bf16_f32 v160, v108, v109
	v_cvt_pk_bf16_f32 v161, v110, v111
	v_cvt_pk_bf16_f32 v162, v104, v105
	v_cvt_pk_bf16_f32 v163, v106, v107
	s_waitcnt vmcnt(16)
	v_lshlrev_b32_e32 v216, 16, v168
	v_and_b32_e32 v217, 0xffff0000, v168
	v_lshlrev_b32_e32 v218, 16, v169
	v_and_b32_e32 v219, 0xffff0000, v169
	v_lshlrev_b32_e32 v220, 16, v170
	v_and_b32_e32 v221, 0xffff0000, v170
	v_lshlrev_b32_e32 v222, 16, v171
	v_and_b32_e32 v223, 0xffff0000, v171
	v_pk_mul_f32 v[76:77], v[76:77], v[216:217]
	v_pk_mul_f32 v[78:79], v[78:79], v[218:219]
	v_pk_mul_f32 v[72:73], v[72:73], v[220:221]
	v_pk_mul_f32 v[74:75], v[74:75], v[222:223]
	v_lshlrev_b32_e32 v216, 16, v172
	v_and_b32_e32 v217, 0xffff0000, v172
	v_lshlrev_b32_e32 v218, 16, v173
	v_and_b32_e32 v219, 0xffff0000, v173
	v_lshlrev_b32_e32 v220, 16, v174
	v_and_b32_e32 v221, 0xffff0000, v174
	v_lshlrev_b32_e32 v222, 16, v175
	v_and_b32_e32 v223, 0xffff0000, v175
	v_pk_add_f32 v[76:77], v[76:77], v[216:217]
	v_pk_add_f32 v[78:79], v[78:79], v[218:219]
	v_pk_add_f32 v[72:73], v[72:73], v[220:221]
	v_pk_add_f32 v[74:75], v[74:75], v[222:223]
	v_cvt_pk_bf16_f32 v168, v76, v77
	v_cvt_pk_bf16_f32 v169, v78, v79
	v_cvt_pk_bf16_f32 v170, v72, v73
	v_cvt_pk_bf16_f32 v171, v74, v75
	s_waitcnt vmcnt(14)
	v_lshlrev_b32_e32 v216, 16, v176
	v_and_b32_e32 v217, 0xffff0000, v176
	v_lshlrev_b32_e32 v218, 16, v177
	v_and_b32_e32 v219, 0xffff0000, v177
	v_lshlrev_b32_e32 v220, 16, v178
	v_and_b32_e32 v221, 0xffff0000, v178
	v_lshlrev_b32_e32 v222, 16, v179
	v_and_b32_e32 v223, 0xffff0000, v179
	v_pk_mul_f32 v[100:101], v[100:101], v[216:217]
	v_pk_mul_f32 v[102:103], v[102:103], v[218:219]
	v_pk_mul_f32 v[96:97], v[96:97], v[220:221]
	v_pk_mul_f32 v[98:99], v[98:99], v[222:223]
	v_lshlrev_b32_e32 v216, 16, v180
	v_and_b32_e32 v217, 0xffff0000, v180
	v_lshlrev_b32_e32 v218, 16, v181
	v_and_b32_e32 v219, 0xffff0000, v181
	v_lshlrev_b32_e32 v220, 16, v182
	v_and_b32_e32 v221, 0xffff0000, v182
	v_lshlrev_b32_e32 v222, 16, v183
	v_and_b32_e32 v223, 0xffff0000, v183
	v_pk_add_f32 v[100:101], v[100:101], v[216:217]
	v_pk_add_f32 v[102:103], v[102:103], v[218:219]
	v_pk_add_f32 v[96:97], v[96:97], v[220:221]
	v_pk_add_f32 v[98:99], v[98:99], v[222:223]
	v_cvt_pk_bf16_f32 v176, v100, v101
	v_cvt_pk_bf16_f32 v177, v102, v103
	v_cvt_pk_bf16_f32 v178, v96, v97
	v_cvt_pk_bf16_f32 v179, v98, v99
	s_waitcnt vmcnt(12)
	v_lshlrev_b32_e32 v216, 16, v184
	v_and_b32_e32 v217, 0xffff0000, v184
	v_lshlrev_b32_e32 v218, 16, v185
	v_and_b32_e32 v219, 0xffff0000, v185
	v_lshlrev_b32_e32 v220, 16, v186
	v_and_b32_e32 v221, 0xffff0000, v186
	v_lshlrev_b32_e32 v222, 16, v187
	v_and_b32_e32 v223, 0xffff0000, v187
	v_pk_mul_f32 v[68:69], v[68:69], v[216:217]
	v_pk_mul_f32 v[70:71], v[70:71], v[218:219]
	v_pk_mul_f32 v[64:65], v[64:65], v[220:221]
	v_pk_mul_f32 v[66:67], v[66:67], v[222:223]
	v_lshlrev_b32_e32 v216, 16, v188
	v_and_b32_e32 v217, 0xffff0000, v188
	v_lshlrev_b32_e32 v218, 16, v189
	v_and_b32_e32 v219, 0xffff0000, v189
	v_lshlrev_b32_e32 v220, 16, v190
	v_and_b32_e32 v221, 0xffff0000, v190
	v_lshlrev_b32_e32 v222, 16, v191
	v_and_b32_e32 v223, 0xffff0000, v191
	v_pk_add_f32 v[68:69], v[68:69], v[216:217]
	v_pk_add_f32 v[70:71], v[70:71], v[218:219]
	v_pk_add_f32 v[64:65], v[64:65], v[220:221]
	v_pk_add_f32 v[66:67], v[66:67], v[222:223]
	v_cvt_pk_bf16_f32 v184, v68, v69
	v_cvt_pk_bf16_f32 v185, v70, v71
	v_cvt_pk_bf16_f32 v186, v64, v65
	v_cvt_pk_bf16_f32 v187, v66, v67
	s_mov_b64 s[10:11], 0x18000
	v_lshl_add_u64 v[224:225], v[214:215], 0, s[10:11]
	global_load_dwordx4 v[108:111], v[224:225], off
	s_mov_b64 s[10:11], 0x50000
	v_lshl_add_u64 v[232:233], v[212:213], 0, s[10:11]
	global_load_dwordx4 v[104:107], v[232:233], off
	s_mov_b64 s[10:11], 0x1a000
	v_lshl_add_u64 v[224:225], v[214:215], 0, s[10:11]
	global_load_dwordx4 v[76:79], v[224:225], off
	s_mov_b64 s[10:11], 0x50000
	v_lshl_add_u64 v[232:233], v[212:213], 0, s[10:11]
	global_load_dwordx4 v[72:75], v[232:233], off offset:256
	s_mov_b64 s[10:11], 0x1c000
	v_lshl_add_u64 v[224:225], v[214:215], 0, s[10:11]
	global_load_dwordx4 v[100:103], v[224:225], off
	s_mov_b64 s[10:11], 0x58000
	v_lshl_add_u64 v[232:233], v[212:213], 0, s[10:11]
	global_load_dwordx4 v[96:99], v[232:233], off
	s_mov_b64 s[10:11], 0x1e000
	v_lshl_add_u64 v[224:225], v[214:215], 0, s[10:11]
	global_load_dwordx4 v[68:71], v[224:225], off
	s_mov_b64 s[10:11], 0x58000
	v_lshl_add_u64 v[232:233], v[212:213], 0, s[10:11]
	global_load_dwordx4 v[64:67], v[232:233], off offset:256
	s_mov_b64 s[10:11], 0x10000
	v_lshl_add_u64 v[224:225], v[212:213], 0, s[10:11]
	global_store_dwordx4 v[224:225], v[160:163], off
	s_mov_b64 s[10:11], 0x10000
	v_lshl_add_u64 v[224:225], v[212:213], 0, s[10:11]
	global_store_dwordx4 v[224:225], v[168:171], off offset:256
	s_mov_b64 s[10:11], 0x18000
	v_lshl_add_u64 v[224:225], v[212:213], 0, s[10:11]
	global_store_dwordx4 v[224:225], v[176:179], off
	s_mov_b64 s[10:11], 0x18000
	v_lshl_add_u64 v[224:225], v[212:213], 0, s[10:11]
	global_store_dwordx4 v[224:225], v[184:187], off offset:256
	s_waitcnt vmcnt(22)
; __device__ __forceinline__ u32x4 pack8(const f32x4& a, const f32x4& b) { u32x4 w; w.x = pk2(a[0], a[1]); w.y = pk2(a[2], a[3]); w.z = pk2(b[0], b[1]); w.w = pk2(b[2], b[3]); return w; }
; __device__ __forceinline__ void unpack8(const u32x4& w, f32x4& a, f32x4& b) { a[0] = bflo(w.x); a[1] = bfhi(w.x); a[2] = bflo(w.y); a[3] = bfhi(w.y); b[0] = bflo(w.z); b[1] = bfhi(w.z); b[2] = bflo(w.w); b[3] = bfhi(w.w); }
;     __device__ __forceinline__ void operator()(const f32x4 (&acc)[2][2][4][2], const Unit& u, int wr, int wc, int fr, int fq) const {
;     ...
;             for (int ai = 0; ai < 2; ++ai) {
;                 u32x4 gw[4][2], pw[4][2];
; #pragma unroll
;                 for (int m = 0; m < 4; ++m)
; #pragma unroll
;                     for (int bj = 0; bj < 2; ++bj) { gw[m][bj] = *(const u32x4*)(tmpb + ((ai * 4 + m) * 2 + bj) * 8192 + voff);
;                         if (br > 0) pw[m][bj] = *(const u32x4*)(MRG + (size_t)(lrow0 + ai * HALF + m * 16) * 1024 + col0 + 128 * bj); }
; #pragma unroll
;                 for (int m = 0; m < 4; ++m)
; #pragma unroll
;                     for (int bj = 0; bj < 2; ++bj) { f32x4 g0, g1; unpack8(gw[m][bj], g0, g1);
;                         f32x4 v0 = acc[ai][bj][m][0] * g0, v1 = acc[ai][bj][m][1] * g1;
;                         if (br > 0) { f32x4 p0, p1; unpack8(pw[m][bj], p0, p1); v0 += p0; v1 += p1; }
;                         *(u32x4*)(MRG + (size_t)(lrow0 + ai * HALF + m * 16) * 1024 + col0 + 128 * bj) = pack8(v0, v1); }
;                 asm volatile("" ::: "memory"); }
	v_lshlrev_b32_e32 v216, 16, v124
	v_and_b32_e32 v217, 0xffff0000, v124
	v_lshlrev_b32_e32 v218, 16, v125
	v_and_b32_e32 v219, 0xffff0000, v125
	v_lshlrev_b32_e32 v220, 16, v126
	v_and_b32_e32 v221, 0xffff0000, v126
	v_lshlrev_b32_e32 v222, 16, v127
	v_and_b32_e32 v223, 0xffff0000, v127
	v_pk_mul_f32 v[60:61], v[60:61], v[216:217]
	v_pk_mul_f32 v[62:63], v[62:63], v[218:219]
	v_pk_mul_f32 v[56:57], v[56:57], v[220:221]
	v_pk_mul_f32 v[58:59], v[58:59], v[222:223]
	v_lshlrev_b32_e32 v216, 16, v120
	v_and_b32_e32 v217, 0xffff0000, v120
	v_lshlrev_b32_e32 v218, 16, v121
	v_and_b32_e32 v219, 0xffff0000, v121
	v_lshlrev_b32_e32 v220, 16, v122
	v_and_b32_e32 v221, 0xffff0000, v122
	v_lshlrev_b32_e32 v222, 16, v123
	v_and_b32_e32 v223, 0xffff0000, v123
	v_pk_add_f32 v[60:61], v[60:61], v[216:217]
	v_pk_add_f32 v[62:63], v[62:63], v[218:219]
	v_pk_add_f32 v[56:57], v[56:57], v[220:221]
	v_pk_add_f32 v[58:59], v[58:59], v[222:223]
	v_cvt_pk_bf16_f32 v124, v60, v61
	v_cvt_pk_bf16_f32 v125, v62, v63
	v_cvt_pk_bf16_f32 v126, v56, v57
	v_cvt_pk_bf16_f32 v127, v58, v59
	s_waitcnt vmcnt(20)
	v_lshlrev_b32_e32 v216, 16, v92
	v_and_b32_e32 v217, 0xffff0000, v92
	v_lshlrev_b32_e32 v218, 16, v93
	v_and_b32_e32 v219, 0xffff0000, v93
	v_lshlrev_b32_e32 v220, 16, v94
	v_and_b32_e32 v221, 0xffff0000, v94
	v_lshlrev_b32_e32 v222, 16, v95
	v_and_b32_e32 v223, 0xffff0000, v95
	v_pk_mul_f32 v[28:29], v[28:29], v[216:217]
	v_pk_mul_f32 v[30:31], v[30:31], v[218:219]
	v_pk_mul_f32 v[24:25], v[24:25], v[220:221]
	v_pk_mul_f32 v[26:27], v[26:27], v[222:223]
	v_lshlrev_b32_e32 v216, 16, v88
	v_and_b32_e32 v217, 0xffff0000, v88
	v_lshlrev_b32_e32 v218, 16, v89
	v_and_b32_e32 v219, 0xffff0000, v89
	v_lshlrev_b32_e32 v220, 16, v90
	v_and_b32_e32 v221, 0xffff0000, v90
	v_lshlrev_b32_e32 v222, 16, v91
	v_and_b32_e32 v223, 0xffff0000, v91
	v_pk_add_f32 v[28:29], v[28:29], v[216:217]
	v_pk_add_f32 v[30:31], v[30:31], v[218:219]
	v_pk_add_f32 v[24:25], v[24:25], v[220:221]
	v_pk_add_f32 v[26:27], v[26:27], v[222:223]
	v_cvt_pk_bf16_f32 v92, v28, v29
	v_cvt_pk_bf16_f32 v93, v30, v31
	v_cvt_pk_bf16_f32 v94, v24, v25
	v_cvt_pk_bf16_f32 v95, v26, v27
	s_waitcnt vmcnt(18)
	v_lshlrev_b32_e32 v216, 16, v116
	v_and_b32_e32 v217, 0xffff0000, v116
	v_lshlrev_b32_e32 v218, 16, v117
	v_and_b32_e32 v219, 0xffff0000, v117
	v_lshlrev_b32_e32 v220, 16, v118
	v_and_b32_e32 v221, 0xffff0000, v118
	v_lshlrev_b32_e32 v222, 16, v119
	v_and_b32_e32 v223, 0xffff0000, v119
	v_pk_mul_f32 v[52:53], v[52:53], v[216:217]
	v_pk_mul_f32 v[54:55], v[54:55], v[218:219]
	v_pk_mul_f32 v[48:49], v[48:49], v[220:221]
	v_pk_mul_f32 v[50:51], v[50:51], v[222:223]
	v_lshlrev_b32_e32 v216, 16, v112
	v_and_b32_e32 v217, 0xffff0000, v112
	v_lshlrev_b32_e32 v218, 16, v113
	v_and_b32_e32 v219, 0xffff0000, v113
	v_lshlrev_b32_e32 v220, 16, v114
	v_and_b32_e32 v221, 0xffff0000, v114
	v_lshlrev_b32_e32 v222, 16, v115
	v_and_b32_e32 v223, 0xffff0000, v115
	v_pk_add_f32 v[52:53], v[52:53], v[216:217]
	v_pk_add_f32 v[54:55], v[54:55], v[218:219]
	v_pk_add_f32 v[48:49], v[48:49], v[220:221]
	v_pk_add_f32 v[50:51], v[50:51], v[222:223]
	v_cvt_pk_bf16_f32 v116, v52, v53
	v_cvt_pk_bf16_f32 v117, v54, v55
	v_cvt_pk_bf16_f32 v118, v48, v49
	v_cvt_pk_bf16_f32 v119, v50, v51
	s_waitcnt vmcnt(16)
	v_lshlrev_b32_e32 v216, 16, v84
	v_and_b32_e32 v217, 0xffff0000, v84
	v_lshlrev_b32_e32 v218, 16, v85
	v_and_b32_e32 v219, 0xffff0000, v85
	v_lshlrev_b32_e32 v220, 16, v86
	v_and_b32_e32 v221, 0xffff0000, v86
	v_lshlrev_b32_e32 v222, 16, v87
	v_and_b32_e32 v223, 0xffff0000, v87
	v_pk_mul_f32 v[20:21], v[20:21], v[216:217]
	v_pk_mul_f32 v[22:23], v[22:23], v[218:219]
	v_pk_mul_f32 v[16:17], v[16:17], v[220:221]
	v_pk_mul_f32 v[18:19], v[18:19], v[222:223]
	v_lshlrev_b32_e32 v216, 16, v80
	v_and_b32_e32 v217, 0xffff0000, v80
	v_lshlrev_b32_e32 v218, 16, v81
	v_and_b32_e32 v219, 0xffff0000, v81
	v_lshlrev_b32_e32 v220, 16, v82
	v_and_b32_e32 v221, 0xffff0000, v82
	v_lshlrev_b32_e32 v222, 16, v83
	v_and_b32_e32 v223, 0xffff0000, v83
	v_pk_add_f32 v[20:21], v[20:21], v[216:217]
	v_pk_add_f32 v[22:23], v[22:23], v[218:219]
	v_pk_add_f32 v[16:17], v[16:17], v[220:221]
	v_pk_add_f32 v[18:19], v[18:19], v[222:223]
	v_cvt_pk_bf16_f32 v84, v20, v21
	v_cvt_pk_bf16_f32 v85, v22, v23
	v_cvt_pk_bf16_f32 v86, v16, v17
	v_cvt_pk_bf16_f32 v87, v18, v19
	s_mov_b64 s[10:11], 0x40000
	v_lshl_add_u64 v[224:225], v[212:213], 0, s[10:11]
	global_store_dwordx4 v[224:225], v[124:127], off
	s_mov_b64 s[10:11], 0x40000
	v_lshl_add_u64 v[224:225], v[212:213], 0, s[10:11]
	global_store_dwordx4 v[224:225], v[92:95], off offset:256
	s_mov_b64 s[10:11], 0x48000
	v_lshl_add_u64 v[224:225], v[212:213], 0, s[10:11]
	global_store_dwordx4 v[224:225], v[116:119], off
	s_mov_b64 s[10:11], 0x48000
	v_lshl_add_u64 v[224:225], v[212:213], 0, s[10:11]
	global_store_dwordx4 v[224:225], v[84:87], off offset:256
	s_waitcnt vmcnt(14)
	v_lshlrev_b32_e32 v216, 16, v108
	v_and_b32_e32 v217, 0xffff0000, v108
	v_lshlrev_b32_e32 v218, 16, v109
	v_and_b32_e32 v219, 0xffff0000, v109
	v_lshlrev_b32_e32 v220, 16, v110
	v_and_b32_e32 v221, 0xffff0000, v110
	v_lshlrev_b32_e32 v222, 16, v111
	v_and_b32_e32 v223, 0xffff0000, v111
	v_pk_mul_f32 v[44:45], v[44:45], v[216:217]
	v_pk_mul_f32 v[46:47], v[46:47], v[218:219]
	v_pk_mul_f32 v[40:41], v[40:41], v[220:221]
	v_pk_mul_f32 v[42:43], v[42:43], v[222:223]
	v_lshlrev_b32_e32 v216, 16, v104
	v_and_b32_e32 v217, 0xffff0000, v104
	v_lshlrev_b32_e32 v218, 16, v105
	v_and_b32_e32 v219, 0xffff0000, v105
	v_lshlrev_b32_e32 v220, 16, v106
	v_and_b32_e32 v221, 0xffff0000, v106
	v_lshlrev_b32_e32 v222, 16, v107
	v_and_b32_e32 v223, 0xffff0000, v107
	v_pk_add_f32 v[44:45], v[44:45], v[216:217]
	v_pk_add_f32 v[46:47], v[46:47], v[218:219]
	v_pk_add_f32 v[40:41], v[40:41], v[220:221]
	v_pk_add_f32 v[42:43], v[42:43], v[222:223]
	v_cvt_pk_bf16_f32 v108, v44, v45
	v_cvt_pk_bf16_f32 v109, v46, v47
	v_cvt_pk_bf16_f32 v110, v40, v41
	v_cvt_pk_bf16_f32 v111, v42, v43
	s_waitcnt vmcnt(12)
; __device__ __forceinline__ u32x4 pack8(const f32x4& a, const f32x4& b) { u32x4 w; w.x = pk2(a[0], a[1]); w.y = pk2(a[2], a[3]); w.z = pk2(b[0], b[1]); w.w = pk2(b[2], b[3]); return w; }
; __device__ __forceinline__ void unpack8(const u32x4& w, f32x4& a, f32x4& b) { a[0] = bflo(w.x); a[1] = bfhi(w.x); a[2] = bflo(w.y); a[3] = bfhi(w.y); b[0] = bflo(w.z); b[1] = bfhi(w.z); b[2] = bflo(w.w); b[3] = bfhi(w.w); }
; __device__ __forceinline__ float row_rstd(const float* ssp, int row, int fq) {
;     const f32x4 t = *((const f32x4*)(ssp + (size_t)row * 16) + fq); float s = (t[0] + t[1]) + (t[2] + t[3]); s += __shfl_xor(s, 16); s += __shfl_xor(s, 32); return rsqrtf(s * (1.0f / DM) + EPS); }
;     __device__ __forceinline__ void operator()(const f32x4 (&acc)[2][2][4][2], const Unit& u, int wr, int wc, int fr, int fq) const {
;     ...
;                     for (int bj = 0; bj < 2; ++bj) { gw[m][bj] = *(const u32x4*)(tmpb + ((ai * 4 + m) * 2 + bj) * 8192 + voff);
;                         if (br > 0) pw[m][bj] = *(const u32x4*)(MRG + (size_t)(lrow0 + ai * HALF + m * 16) * 1024 + col0 + 128 * bj); }
; #pragma unroll
;                 for (int m = 0; m < 4; ++m)
; #pragma unroll
;                     for (int bj = 0; bj < 2; ++bj) { f32x4 g0, g1; unpack8(gw[m][bj], g0, g1);
;                         f32x4 v0 = acc[ai][bj][m][0] * g0, v1 = acc[ai][bj][m][1] * g1;
;                         if (br > 0) { f32x4 p0, p1; unpack8(pw[m][bj], p0, p1); v0 += p0; v1 += p1; }
;                         *(u32x4*)(MRG + (size_t)(lrow0 + ai * HALF + m * 16) * 1024 + col0 + 128 * bj) = pack8(v0, v1); }
	v_lshlrev_b32_e32 v216, 16, v76
	v_and_b32_e32 v217, 0xffff0000, v76
	v_lshlrev_b32_e32 v218, 16, v77
	v_and_b32_e32 v219, 0xffff0000, v77
	v_lshlrev_b32_e32 v220, 16, v78
	v_and_b32_e32 v221, 0xffff0000, v78
	v_lshlrev_b32_e32 v222, 16, v79
	v_and_b32_e32 v223, 0xffff0000, v79
	v_pk_mul_f32 v[12:13], v[12:13], v[216:217]
	v_pk_mul_f32 v[14:15], v[14:15], v[218:219]
	v_pk_mul_f32 v[8:9], v[8:9], v[220:221]
	v_pk_mul_f32 v[10:11], v[10:11], v[222:223]
	v_lshlrev_b32_e32 v216, 16, v72
	v_and_b32_e32 v217, 0xffff0000, v72
	v_lshlrev_b32_e32 v218, 16, v73
	v_and_b32_e32 v219, 0xffff0000, v73
	v_lshlrev_b32_e32 v220, 16, v74
	v_and_b32_e32 v221, 0xffff0000, v74
	v_lshlrev_b32_e32 v222, 16, v75
	v_and_b32_e32 v223, 0xffff0000, v75
	v_pk_add_f32 v[12:13], v[12:13], v[216:217]
	v_pk_add_f32 v[14:15], v[14:15], v[218:219]
	v_pk_add_f32 v[8:9], v[8:9], v[220:221]
	v_pk_add_f32 v[10:11], v[10:11], v[222:223]
	v_cvt_pk_bf16_f32 v76, v12, v13
	v_cvt_pk_bf16_f32 v77, v14, v15
	v_cvt_pk_bf16_f32 v78, v8, v9
	v_cvt_pk_bf16_f32 v79, v10, v11
	s_waitcnt vmcnt(10)
	v_lshlrev_b32_e32 v216, 16, v100
	v_and_b32_e32 v217, 0xffff0000, v100
	v_lshlrev_b32_e32 v218, 16, v101
	v_and_b32_e32 v219, 0xffff0000, v101
	v_lshlrev_b32_e32 v220, 16, v102
	v_and_b32_e32 v221, 0xffff0000, v102
	v_lshlrev_b32_e32 v222, 16, v103
	v_and_b32_e32 v223, 0xffff0000, v103
	v_pk_mul_f32 v[36:37], v[36:37], v[216:217]
	v_pk_mul_f32 v[38:39], v[38:39], v[218:219]
	v_pk_mul_f32 v[32:33], v[32:33], v[220:221]
	v_pk_mul_f32 v[34:35], v[34:35], v[222:223]
	v_lshlrev_b32_e32 v216, 16, v96
	v_and_b32_e32 v217, 0xffff0000, v96
	v_lshlrev_b32_e32 v218, 16, v97
	v_and_b32_e32 v219, 0xffff0000, v97
	v_lshlrev_b32_e32 v220, 16, v98
	v_and_b32_e32 v221, 0xffff0000, v98
	v_lshlrev_b32_e32 v222, 16, v99
	v_and_b32_e32 v223, 0xffff0000, v99
	v_pk_add_f32 v[36:37], v[36:37], v[216:217]
	v_pk_add_f32 v[38:39], v[38:39], v[218:219]
	v_pk_add_f32 v[32:33], v[32:33], v[220:221]
	v_pk_add_f32 v[34:35], v[34:35], v[222:223]
	v_cvt_pk_bf16_f32 v100, v36, v37
	v_cvt_pk_bf16_f32 v101, v38, v39
	v_cvt_pk_bf16_f32 v102, v32, v33
	v_cvt_pk_bf16_f32 v103, v34, v35
	s_waitcnt vmcnt(8)
	v_lshlrev_b32_e32 v216, 16, v68
	v_and_b32_e32 v217, 0xffff0000, v68
	v_lshlrev_b32_e32 v218, 16, v69
	v_and_b32_e32 v219, 0xffff0000, v69
	v_lshlrev_b32_e32 v220, 16, v70
	v_and_b32_e32 v221, 0xffff0000, v70
	v_lshlrev_b32_e32 v222, 16, v71
	v_and_b32_e32 v223, 0xffff0000, v71
	v_pk_mul_f32 v[4:5], v[4:5], v[216:217]
	v_pk_mul_f32 v[6:7], v[6:7], v[218:219]
	v_pk_mul_f32 v[0:1], v[0:1], v[220:221]
	v_pk_mul_f32 v[2:3], v[2:3], v[222:223]
	v_lshlrev_b32_e32 v216, 16, v64
	v_and_b32_e32 v217, 0xffff0000, v64
	v_lshlrev_b32_e32 v218, 16, v65
	v_and_b32_e32 v219, 0xffff0000, v65
	v_lshlrev_b32_e32 v220, 16, v66
	v_and_b32_e32 v221, 0xffff0000, v66
	v_lshlrev_b32_e32 v222, 16, v67
	v_and_b32_e32 v223, 0xffff0000, v67
	v_pk_add_f32 v[4:5], v[4:5], v[216:217]
	v_pk_add_f32 v[6:7], v[6:7], v[218:219]
	v_pk_add_f32 v[0:1], v[0:1], v[220:221]
	v_pk_add_f32 v[2:3], v[2:3], v[222:223]
	v_cvt_pk_bf16_f32 v68, v4, v5
	v_cvt_pk_bf16_f32 v69, v6, v7
	v_cvt_pk_bf16_f32 v70, v0, v1
	v_cvt_pk_bf16_f32 v71, v2, v3
	s_mov_b64 s[10:11], 0x50000
	v_lshl_add_u64 v[224:225], v[212:213], 0, s[10:11]
	global_store_dwordx4 v[224:225], v[108:111], off
	s_mov_b64 s[10:11], 0x50000
	v_lshl_add_u64 v[224:225], v[212:213], 0, s[10:11]
	global_store_dwordx4 v[224:225], v[76:79], off offset:256
	s_mov_b64 s[10:11], 0x58000
	v_lshl_add_u64 v[224:225], v[212:213], 0, s[10:11]
	global_store_dwordx4 v[224:225], v[100:103], off
	s_mov_b64 s[10:11], 0x58000
	v_lshl_add_u64 v[224:225], v[212:213], 0, s[10:11]
	global_store_dwordx4 v[224:225], v[68:71], off offset:256
.Le2_done:
	s_mov_b64 s[18:19], 0
.LBB0_558:
	s_and_b64 vcc, exec, s[18:19]
	s_cbranch_vccz .LBB0_560
	v_and_b32_e32 v129, 64, v229
	v_xor_b32_e32 v128, 16, v229
	v_add_u32_e32 v129, 64, v129
	v_cmp_lt_i32_e32 vcc, v128, v129
	v_ashrrev_i32_e32 v211, 31, v210
	s_mov_b32 s10, 0x358637bd
	v_cndmask_b32_e32 v128, v229, v128, vcc
	v_lshlrev_b32_e32 v140, 2, v128
	v_xor_b32_e32 v128, 32, v229
	v_cmp_lt_i32_e32 vcc, v128, v129
	v_mov_b32_e32 v209, v193
	s_nop 0
	v_cndmask_b32_e32 v128, v229, v128, vcc
	v_lshlrev_b32_e32 v141, 2, v128
	v_lshlrev_b64 v[128:129], 6, v[210:211]
	v_lshl_add_u64 v[130:131], v[202:203], 0, v[128:129]
	global_load_dwordx4 v[156:159], v[130:131], off
	global_load_dwordx4 v[160:163], v[130:131], off offset:1024
	global_load_dwordx4 v[164:167], v[130:131], off offset:2048
	global_load_dwordx4 v[168:171], v[130:131], off offset:3072
	v_add_co_u32_e32 v188, vcc, 0x2000, v130
	s_nop 1
	v_addc_co_u32_e32 v189, vcc, 0, v131, vcc
	global_load_dwordx4 v[172:175], v[188:189], off
	global_load_dwordx4 v[176:179], v[188:189], off offset:1024
	global_load_dwordx4 v[180:183], v[188:189], off offset:2048
	global_load_dwordx4 v[184:187], v[188:189], off offset:3072
	s_waitcnt vmcnt(7)
	v_mov_b32_e32 v128, v157
	v_mov_b32_e32 v129, v158
	v_mov_b32_e32 v157, v159
	v_pk_add_f32 v[128:129], v[128:129], v[156:157]
	s_waitcnt vmcnt(6)
	v_mov_b32_e32 v136, v161
	v_mov_b32_e32 v137, v162
	v_mov_b32_e32 v161, v163
	v_pk_add_f32 v[132:133], v[136:137], v[160:161]
	v_mov_b32_e32 v135, v128
	v_mov_b32_e32 v134, v132
	v_mov_b32_e32 v128, v133
	v_pk_add_f32 v[128:129], v[134:135], v[128:129]
	ds_bpermute_b32 v133, v140, v129
	ds_bpermute_b32 v132, v140, v128
	s_waitcnt lgkmcnt(0)
	v_pk_add_f32 v[128:129], v[128:129], v[132:133]
	ds_bpermute_b32 v133, v141, v129
	ds_bpermute_b32 v132, v141, v128
	s_waitcnt lgkmcnt(0)
; __device__ __forceinline__ float row_rstd(const float* ssp, int row, int fq) {
;     const f32x4 t = *((const f32x4*)(ssp + (size_t)row * 16) + fq); float s = (t[0] + t[1]) + (t[2] + t[3]); s += __shfl_xor(s, 16); s += __shfl_xor(s, 32); return rsqrtf(s * (1.0f / DM) + EPS); }
;     __device__ __forceinline__ void operator()(const f32x4 (&acc)[2][2][4][2], const Unit& u, int wr, int wc, int fr, int fq) const {
;     ...
;             float rx[2][4];
; #pragma unroll
;             for (int ai = 0; ai < 2; ++ai)
; #pragma unroll
;                 for (int m = 0; m < 4; ++m) rx[ai][m] = row_rstd(ssp, row0 + ai * HALF + m * 16, fq);
; #pragma unroll
;             for (int bj = 0; bj < 2; ++bj) {
;                 const f32x4 bv0 = *(const f32x4*)(gb + br * 1024 + col0 + 128 * bj), bv1 = *(const f32x4*)(gb + br * 1024 + col0 + 128 * bj + 4);
	v_pk_add_f32 v[132:133], v[128:129], v[132:133]
	v_mov_b64_e32 v[128:129], s[10:11]
	v_pk_fma_f32 v[132:133], v[132:133], s[38:39], v[128:129] op_sel_hi:[1,0,0]
	s_and_b32 s10, 0xffff, s52
	v_mul_f32_e32 v134, 0x4b800000, v133
	v_cmp_gt_f32_e64 s[42:43], s99, v133
	v_cmp_gt_f32_e32 vcc, s99, v132
	s_lshl_b32 s10, s10, 12
	v_cndmask_b32_e64 v133, v133, v134, s[42:43]
	v_rsq_f32_e32 v133, v133
	s_add_u32 s10, s63, s10
	s_addc_u32 s11, s64, 0
	v_mul_f32_e32 v134, 0x45800000, v133
	v_cndmask_b32_e64 v147, v133, v134, s[42:43]
	v_mul_f32_e32 v133, 0x4b800000, v132
	v_cndmask_b32_e32 v132, v132, v133, vcc
	v_rsq_f32_e32 v132, v132
	s_nop 0
	v_mul_f32_e32 v133, 0x45800000, v132
	v_cndmask_b32_e32 v145, v132, v133, vcc
	s_waitcnt vmcnt(5)
	v_mov_b32_e32 v136, v165
	v_mov_b32_e32 v137, v166
	v_mov_b32_e32 v165, v167
	v_pk_add_f32 v[136:137], v[136:137], v[164:165]
	s_waitcnt vmcnt(4)
	v_mov_b32_e32 v138, v169
	v_mov_b32_e32 v139, v170
	v_mov_b32_e32 v169, v171
	v_pk_add_f32 v[132:133], v[138:139], v[168:169]
	v_mov_b32_e32 v135, v136
	v_mov_b32_e32 v134, v132
	v_mov_b32_e32 v136, v133
	v_pk_add_f32 v[132:133], v[134:135], v[136:137]
	ds_bpermute_b32 v135, v140, v133
	ds_bpermute_b32 v134, v140, v132
	s_waitcnt lgkmcnt(0)
	v_pk_add_f32 v[132:133], v[132:133], v[134:135]
	ds_bpermute_b32 v135, v141, v133
	ds_bpermute_b32 v134, v141, v132
	s_waitcnt lgkmcnt(0)
	v_pk_add_f32 v[132:133], v[132:133], v[134:135]
	s_nop 0
	v_pk_fma_f32 v[132:133], v[132:133], s[38:39], v[128:129] op_sel_hi:[1,0,0]
	s_nop 0
	v_mul_f32_e32 v134, 0x4b800000, v133
	v_cmp_gt_f32_e64 s[42:43], s99, v133
	v_cmp_gt_f32_e32 vcc, s99, v132
	s_nop 0
	v_cndmask_b32_e64 v133, v133, v134, s[42:43]
	v_rsq_f32_e32 v133, v133
	s_nop 0
	v_mul_f32_e32 v134, 0x45800000, v133
	v_cndmask_b32_e64 v146, v133, v134, s[42:43]
	v_mul_f32_e32 v133, 0x4b800000, v132
	v_cndmask_b32_e32 v132, v132, v133, vcc
	v_rsq_f32_e32 v132, v132
	s_nop 0
	v_mul_f32_e32 v133, 0x45800000, v132
	v_cndmask_b32_e32 v143, v132, v133, vcc
	s_waitcnt vmcnt(3)
	v_mov_b32_e32 v136, v173
	v_mov_b32_e32 v137, v174
	v_mov_b32_e32 v173, v175
	v_pk_add_f32 v[136:137], v[136:137], v[172:173]
	s_waitcnt vmcnt(2)
	v_mov_b32_e32 v138, v177
	v_mov_b32_e32 v139, v178
	v_mov_b32_e32 v177, v179
	v_pk_add_f32 v[130:131], v[138:139], v[176:177]
	v_mov_b32_e32 v133, v136
	v_mov_b32_e32 v132, v130
	v_mov_b32_e32 v136, v131
	v_pk_add_f32 v[130:131], v[132:133], v[136:137]
	ds_bpermute_b32 v133, v140, v131
	ds_bpermute_b32 v132, v140, v130
	v_lshl_add_u64 v[138:139], v[208:209], 2, s[10:11]
	s_mov_b32 s10, 0x8000
	s_waitcnt lgkmcnt(0)
	v_pk_add_f32 v[130:131], v[130:131], v[132:133]
	ds_bpermute_b32 v133, v141, v131
	ds_bpermute_b32 v132, v141, v130
	s_waitcnt lgkmcnt(0)
	v_pk_add_f32 v[130:131], v[130:131], v[132:133]
	s_nop 0
	v_pk_fma_f32 v[130:131], v[130:131], s[38:39], v[128:129] op_sel_hi:[1,0,0]
	s_nop 0
	v_mul_f32_e32 v132, 0x4b800000, v131
	v_cmp_gt_f32_e64 s[42:43], s99, v131
	v_cmp_gt_f32_e32 vcc, s99, v130
	s_nop 0
	v_cndmask_b32_e64 v131, v131, v132, s[42:43]
	v_rsq_f32_e32 v131, v131
	s_nop 0
	v_mul_f32_e32 v132, 0x45800000, v131
	v_cndmask_b32_e64 v144, v131, v132, s[42:43]
	v_mul_f32_e32 v131, 0x4b800000, v130
	v_cndmask_b32_e32 v130, v130, v131, vcc
	v_rsq_f32_e32 v130, v130
	s_nop 0
	v_mul_f32_e32 v131, 0x45800000, v130
	v_cndmask_b32_e32 v142, v130, v131, vcc
	s_waitcnt vmcnt(1)
	v_mov_b32_e32 v136, v181
	v_mov_b32_e32 v137, v182
	v_mov_b32_e32 v181, v183
	v_pk_add_f32 v[136:137], v[136:137], v[180:181]
	s_waitcnt vmcnt(0)
	v_mov_b32_e32 v134, v185
	v_mov_b32_e32 v135, v186
	v_mov_b32_e32 v185, v187
	v_pk_add_f32 v[130:131], v[134:135], v[184:185]
	v_mov_b32_e32 v133, v136
	v_mov_b32_e32 v132, v130
	v_mov_b32_e32 v136, v131
	v_pk_add_f32 v[130:131], v[132:133], v[136:137]
	ds_bpermute_b32 v133, v140, v131
	ds_bpermute_b32 v132, v140, v130
	v_lshl_add_u64 v[136:137], s[30:31], 0, v[192:193]
	s_waitcnt lgkmcnt(0)
	v_pk_add_f32 v[130:131], v[130:131], v[132:133]
	ds_bpermute_b32 v133, v141, v131
	ds_bpermute_b32 v132, v141, v130
	s_waitcnt lgkmcnt(0)
	v_pk_add_f32 v[130:131], v[130:131], v[132:133]
	s_nop 0
	v_pk_fma_f32 v[128:129], v[130:131], s[38:39], v[128:129] op_sel_hi:[1,0,0]
	s_nop 0
	v_mul_f32_e32 v130, 0x4b800000, v129
	v_cmp_gt_f32_e64 s[42:43], s99, v129
	v_cmp_gt_f32_e32 vcc, s99, v128
	s_nop 0
	v_cndmask_b32_e64 v129, v129, v130, s[42:43]
	v_rsq_f32_e32 v129, v129
	s_nop 0
	v_mul_f32_e32 v130, 0x45800000, v129
	v_cndmask_b32_e64 v141, v129, v130, s[42:43]
	v_mul_f32_e32 v129, 0x4b800000, v128
	v_cndmask_b32_e32 v128, v128, v129, vcc
	v_rsq_f32_e32 v128, v128
	s_nop 0
	v_mul_f32_e32 v129, 0x45800000, v128
	v_cndmask_b32_e32 v140, v128, v129, vcc
	global_load_dwordx4 v[128:131], v[138:139], off offset:16
	global_load_dwordx4 v[132:135], v[138:139], off
	global_load_dwordx4 v[156:159], v[138:139], off offset:528
	global_load_dwordx4 v[160:163], v[138:139], off offset:512
	s_waitcnt vmcnt(3)
	v_fma_f32 v149, v120, v147, v128
	v_mul_f32_e32 v149, 0xbfb8aa3b, v149
	v_exp_f32_e32 v149, v149
	s_waitcnt vmcnt(2)
; __device__ __forceinline__ u32x4 pack8(const f32x4& a, const f32x4& b) { u32x4 w; w.x = pk2(a[0], a[1]); w.y = pk2(a[2], a[3]); w.z = pk2(b[0], b[1]); w.w = pk2(b[2], b[3]); return w; }
; __device__ __forceinline__ float sigm(float x) { return __builtin_amdgcn_rcpf(1.0f + __builtin_amdgcn_exp2f(x * -1.4426950408889634f)); }
;     __device__ __forceinline__ void operator()(const f32x4 (&acc)[2][2][4][2], const Unit& u, int wr, int wc, int fr, int fq) const {
;     ...
;                 for (int ai = 0; ai < 2; ++ai)
; #pragma unroll
;                     for (int m = 0; m < 4; ++m) {
;                         const f32x4 a0 = acc[ai][bj][m][0] * rx[ai][m] + bv0, a1 = acc[ai][bj][m][1] * rx[ai][m] + bv1; f32x4 o0, o1;
; #pragma unroll
;                         for (int e = 0; e < 4; ++e) { o0[e] = sigm(a0[e]); o1[e] = sigm(a1[e]); }
;                         *(u32x4*)(tmpb + ((ai * 4 + m) * 2 + bj) * 8192 + voff) = pack8(o0, o1); }
	v_fma_f32 v148, v124, v147, v132
	v_fma_f32 v151, v121, v147, v129
	v_fma_f32 v152, v126, v147, v134
	v_add_f32_e32 v149, 1.0, v149
	v_rcp_f32_e32 v150, v149
	v_fma_f32 v149, v125, v147, v133
	v_fma_f32 v153, v122, v147, v130
	v_fma_f32 v154, v127, v147, v135
	v_fma_f32 v155, v123, v147, v131
	v_mul_f32_e32 v148, 0xbfb8aa3b, v148
	v_mul_f32_e32 v149, 0xbfb8aa3b, v149
	v_mul_f32_e32 v151, 0xbfb8aa3b, v151
	v_mul_f32_e32 v152, 0xbfb8aa3b, v152
	v_mul_f32_e32 v153, 0xbfb8aa3b, v153
	v_mul_f32_e32 v154, 0xbfb8aa3b, v154
	v_mul_f32_e32 v155, 0xbfb8aa3b, v155
	v_exp_f32_e32 v148, v148
	v_exp_f32_e32 v149, v149
	v_exp_f32_e32 v151, v151
	v_exp_f32_e32 v152, v152
	v_exp_f32_e32 v153, v153
	v_exp_f32_e32 v154, v154
	v_exp_f32_e32 v155, v155
	v_add_f32_e32 v148, 1.0, v148
	v_add_f32_e32 v149, 1.0, v149
	v_add_f32_e32 v151, 1.0, v151
	v_add_f32_e32 v152, 1.0, v152
	v_add_f32_e32 v153, 1.0, v153
	v_add_f32_e32 v154, 1.0, v154
	v_add_f32_e32 v155, 1.0, v155
	v_rcp_f32_e32 v148, v148
	v_rcp_f32_e32 v149, v149
	v_rcp_f32_e32 v151, v151
	v_rcp_f32_e32 v152, v152
	v_rcp_f32_e32 v153, v153
	v_rcp_f32_e32 v154, v154
	v_rcp_f32_e32 v155, v155
	v_cvt_pk_bf16_f32 v148, v148, v149
	v_cvt_pk_bf16_f32 v150, v150, v151
	v_cvt_pk_bf16_f32 v149, v152, v154
	v_cvt_pk_bf16_f32 v151, v153, v155
	global_store_dwordx4 v192, v[148:151], s[30:31]
	v_fma_f32 v152, v118, v145, v134
	v_fma_f32 v154, v119, v145, v135
	v_fma_f32 v149, v112, v145, v128
	v_mul_f32_e32 v149, 0xbfb8aa3b, v149
	v_exp_f32_e32 v149, v149
	v_fma_f32 v148, v116, v145, v132
	v_mul_f32_e32 v148, 0xbfb8aa3b, v148
	v_fma_f32 v151, v113, v145, v129
	v_add_f32_e32 v149, 1.0, v149
	v_rcp_f32_e32 v150, v149
	v_fma_f32 v149, v117, v145, v133
	v_mul_f32_e32 v149, 0xbfb8aa3b, v149
	v_mul_f32_e32 v152, 0xbfb8aa3b, v152
	v_fma_f32 v153, v114, v145, v130
	v_mul_f32_e32 v154, 0xbfb8aa3b, v154
	v_fma_f32 v155, v115, v145, v131
	v_exp_f32_e32 v148, v148
	v_exp_f32_e32 v149, v149
	v_mul_f32_e32 v151, 0xbfb8aa3b, v151
	v_exp_f32_e32 v152, v152
	v_mul_f32_e32 v153, 0xbfb8aa3b, v153
	v_exp_f32_e32 v154, v154
	v_mul_f32_e32 v155, 0xbfb8aa3b, v155
	v_exp_f32_e32 v151, v151
	v_exp_f32_e32 v153, v153
	v_exp_f32_e32 v155, v155
	v_add_f32_e32 v148, 1.0, v148
	v_add_f32_e32 v149, 1.0, v149
	v_add_f32_e32 v152, 1.0, v152
	v_add_f32_e32 v154, 1.0, v154
	v_rcp_f32_e32 v148, v148
	v_rcp_f32_e32 v149, v149
	v_add_f32_e32 v151, 1.0, v151
	v_rcp_f32_e32 v152, v152
	v_add_f32_e32 v153, 1.0, v153
	v_rcp_f32_e32 v154, v154
	v_add_f32_e32 v155, 1.0, v155
	v_rcp_f32_e32 v151, v151
	v_rcp_f32_e32 v153, v153
	v_rcp_f32_e32 v155, v155
	v_cvt_pk_bf16_f32 v148, v148, v149
	v_cvt_pk_bf16_f32 v149, v152, v154
	v_add_co_u32_e32 v152, vcc, s83, v136
	v_cvt_pk_bf16_f32 v150, v150, v151
	v_cvt_pk_bf16_f32 v151, v153, v155
	v_addc_co_u32_e32 v153, vcc, 0, v137, vcc
	global_store_dwordx4 v[152:153], v[148:151], off
	v_fma_f32 v152, v110, v146, v134
	v_fma_f32 v154, v111, v146, v135
	v_fma_f32 v149, v104, v146, v128
	v_mul_f32_e32 v149, 0xbfb8aa3b, v149
	v_exp_f32_e32 v149, v149
	v_fma_f32 v148, v108, v146, v132
	v_mul_f32_e32 v148, 0xbfb8aa3b, v148
	v_fma_f32 v151, v105, v146, v129
	v_add_f32_e32 v149, 1.0, v149
	v_rcp_f32_e32 v150, v149
	v_fma_f32 v149, v109, v146, v133
	v_mul_f32_e32 v149, 0xbfb8aa3b, v149
	v_mul_f32_e32 v152, 0xbfb8aa3b, v152
	v_fma_f32 v153, v106, v146, v130
	v_mul_f32_e32 v154, 0xbfb8aa3b, v154
	v_fma_f32 v155, v107, v146, v131
	v_exp_f32_e32 v148, v148
	v_exp_f32_e32 v149, v149
	v_mul_f32_e32 v151, 0xbfb8aa3b, v151
	v_exp_f32_e32 v152, v152
	v_mul_f32_e32 v153, 0xbfb8aa3b, v153
	v_exp_f32_e32 v154, v154
	v_mul_f32_e32 v155, 0xbfb8aa3b, v155
	v_exp_f32_e32 v151, v151
	v_exp_f32_e32 v153, v153
	v_exp_f32_e32 v155, v155
	v_add_f32_e32 v148, 1.0, v148
	v_add_f32_e32 v149, 1.0, v149
	v_add_f32_e32 v152, 1.0, v152
	v_add_f32_e32 v154, 1.0, v154
	v_rcp_f32_e32 v148, v148
	v_rcp_f32_e32 v149, v149
	v_add_f32_e32 v151, 1.0, v151
	v_rcp_f32_e32 v152, v152
	v_add_f32_e32 v153, 1.0, v153
	v_rcp_f32_e32 v154, v154
	v_add_f32_e32 v155, 1.0, v155
	v_rcp_f32_e32 v151, v151
	v_rcp_f32_e32 v153, v153
	v_rcp_f32_e32 v155, v155
	v_cvt_pk_bf16_f32 v148, v148, v149
	v_cvt_pk_bf16_f32 v149, v152, v154
	v_add_co_u32_e32 v152, vcc, s10, v136
	v_cvt_pk_bf16_f32 v150, v150, v151
	v_cvt_pk_bf16_f32 v151, v153, v155
	v_addc_co_u32_e32 v153, vcc, 0, v137, vcc
	global_store_dwordx4 v[152:153], v[148:151], off
	v_fma_f32 v152, v102, v143, v134
	v_fma_f32 v154, v103, v143, v135
	v_fma_f32 v149, v96, v143, v128
	v_mul_f32_e32 v149, 0xbfb8aa3b, v149
	v_exp_f32_e32 v149, v149
	v_fma_f32 v148, v100, v143, v132
	v_mul_f32_e32 v148, 0xbfb8aa3b, v148
	v_fma_f32 v151, v97, v143, v129
	v_add_f32_e32 v149, 1.0, v149
	v_rcp_f32_e32 v150, v149
	v_fma_f32 v149, v101, v143, v133
	v_mul_f32_e32 v149, 0xbfb8aa3b, v149
	v_mul_f32_e32 v152, 0xbfb8aa3b, v152
	v_fma_f32 v153, v98, v143, v130
	v_mul_f32_e32 v154, 0xbfb8aa3b, v154
	v_fma_f32 v155, v99, v143, v131
	v_exp_f32_e32 v148, v148
	v_exp_f32_e32 v149, v149
	v_mul_f32_e32 v151, 0xbfb8aa3b, v151
	v_exp_f32_e32 v152, v152
	v_mul_f32_e32 v153, 0xbfb8aa3b, v153
	v_exp_f32_e32 v154, v154
	v_mul_f32_e32 v155, 0xbfb8aa3b, v155
	v_exp_f32_e32 v151, v151
	v_exp_f32_e32 v153, v153
	v_exp_f32_e32 v155, v155
	v_add_f32_e32 v148, 1.0, v148
	v_add_f32_e32 v149, 1.0, v149
	v_add_f32_e32 v152, 1.0, v152
	v_add_f32_e32 v154, 1.0, v154
	v_rcp_f32_e32 v148, v148
	v_rcp_f32_e32 v149, v149
	v_add_f32_e32 v151, 1.0, v151
	v_rcp_f32_e32 v152, v152
	v_add_f32_e32 v153, 1.0, v153
	v_rcp_f32_e32 v154, v154
	v_add_f32_e32 v155, 1.0, v155
	v_rcp_f32_e32 v151, v151
	v_rcp_f32_e32 v153, v153
	v_rcp_f32_e32 v155, v155
	s_mov_b32 s10, 0xc000
; __device__ __forceinline__ u32x4 pack8(const f32x4& a, const f32x4& b) { u32x4 w; w.x = pk2(a[0], a[1]); w.y = pk2(a[2], a[3]); w.z = pk2(b[0], b[1]); w.w = pk2(b[2], b[3]); return w; }
; __device__ __forceinline__ float sigm(float x) { return __builtin_amdgcn_rcpf(1.0f + __builtin_amdgcn_exp2f(x * -1.4426950408889634f)); }
;     __device__ __forceinline__ void operator()(const f32x4 (&acc)[2][2][4][2], const Unit& u, int wr, int wc, int fr, int fq) const {
;     ...
;                 for (int ai = 0; ai < 2; ++ai)
; #pragma unroll
;                     for (int m = 0; m < 4; ++m) {
;                         const f32x4 a0 = acc[ai][bj][m][0] * rx[ai][m] + bv0, a1 = acc[ai][bj][m][1] * rx[ai][m] + bv1; f32x4 o0, o1;
; #pragma unroll
;                         for (int e = 0; e < 4; ++e) { o0[e] = sigm(a0[e]); o1[e] = sigm(a1[e]); }
;                         *(u32x4*)(tmpb + ((ai * 4 + m) * 2 + bj) * 8192 + voff) = pack8(o0, o1); }
	v_cvt_pk_bf16_f32 v148, v148, v149
	v_cvt_pk_bf16_f32 v149, v152, v154
	v_add_co_u32_e32 v152, vcc, s10, v136
	v_cvt_pk_bf16_f32 v150, v150, v151
	v_cvt_pk_bf16_f32 v151, v153, v155
	v_addc_co_u32_e32 v153, vcc, 0, v137, vcc
	global_store_dwordx4 v[152:153], v[148:151], off
	v_fma_f32 v152, v62, v144, v134
	v_fma_f32 v154, v63, v144, v135
	v_fma_f32 v149, v56, v144, v128
	v_mul_f32_e32 v149, 0xbfb8aa3b, v149
	v_exp_f32_e32 v149, v149
	v_fma_f32 v148, v60, v144, v132
	v_mul_f32_e32 v148, 0xbfb8aa3b, v148
	v_fma_f32 v151, v57, v144, v129
	v_add_f32_e32 v149, 1.0, v149
	v_rcp_f32_e32 v150, v149
	v_fma_f32 v149, v61, v144, v133
	v_mul_f32_e32 v149, 0xbfb8aa3b, v149
	v_mul_f32_e32 v152, 0xbfb8aa3b, v152
	v_fma_f32 v153, v58, v144, v130
	v_mul_f32_e32 v154, 0xbfb8aa3b, v154
	v_fma_f32 v155, v59, v144, v131
	v_exp_f32_e32 v148, v148
	v_exp_f32_e32 v149, v149
	v_mul_f32_e32 v151, 0xbfb8aa3b, v151
	v_exp_f32_e32 v152, v152
	v_mul_f32_e32 v153, 0xbfb8aa3b, v153
	v_exp_f32_e32 v154, v154
	v_mul_f32_e32 v155, 0xbfb8aa3b, v155
	v_exp_f32_e32 v151, v151
	v_exp_f32_e32 v153, v153
	v_exp_f32_e32 v155, v155
	v_add_f32_e32 v148, 1.0, v148
	v_add_f32_e32 v149, 1.0, v149
	v_add_f32_e32 v152, 1.0, v152
	v_add_f32_e32 v154, 1.0, v154
	v_rcp_f32_e32 v148, v148
	v_rcp_f32_e32 v149, v149
	v_add_f32_e32 v151, 1.0, v151
	v_rcp_f32_e32 v152, v152
	v_add_f32_e32 v153, 1.0, v153
	v_rcp_f32_e32 v154, v154
	v_add_f32_e32 v155, 1.0, v155
	v_rcp_f32_e32 v151, v151
	v_rcp_f32_e32 v153, v153
	v_rcp_f32_e32 v155, v155
	v_cvt_pk_bf16_f32 v148, v148, v149
	v_cvt_pk_bf16_f32 v149, v152, v154
	v_add_co_u32_e32 v152, vcc, s4, v136
	v_cvt_pk_bf16_f32 v150, v150, v151
	v_cvt_pk_bf16_f32 v151, v153, v155
	v_addc_co_u32_e32 v153, vcc, 0, v137, vcc
	global_store_dwordx4 v[152:153], v[148:151], off
	v_fma_f32 v152, v54, v142, v134
	v_fma_f32 v154, v55, v142, v135
	v_fma_f32 v149, v48, v142, v128
	v_mul_f32_e32 v149, 0xbfb8aa3b, v149
	v_exp_f32_e32 v149, v149
	v_fma_f32 v148, v52, v142, v132
	v_mul_f32_e32 v148, 0xbfb8aa3b, v148
	v_fma_f32 v151, v49, v142, v129
	v_add_f32_e32 v149, 1.0, v149
	v_rcp_f32_e32 v150, v149
	v_fma_f32 v149, v53, v142, v133
	v_mul_f32_e32 v149, 0xbfb8aa3b, v149
	v_mul_f32_e32 v152, 0xbfb8aa3b, v152
	v_fma_f32 v153, v50, v142, v130
	v_mul_f32_e32 v154, 0xbfb8aa3b, v154
	v_fma_f32 v155, v51, v142, v131
	v_exp_f32_e32 v148, v148
	v_exp_f32_e32 v149, v149
	v_mul_f32_e32 v151, 0xbfb8aa3b, v151
	v_exp_f32_e32 v152, v152
	v_mul_f32_e32 v153, 0xbfb8aa3b, v153
	v_exp_f32_e32 v154, v154
	v_mul_f32_e32 v155, 0xbfb8aa3b, v155
	v_exp_f32_e32 v151, v151
	v_exp_f32_e32 v153, v153
	v_exp_f32_e32 v155, v155
	v_add_f32_e32 v148, 1.0, v148
	v_add_f32_e32 v149, 1.0, v149
	v_add_f32_e32 v152, 1.0, v152
	v_add_f32_e32 v154, 1.0, v154
	v_rcp_f32_e32 v148, v148
	v_rcp_f32_e32 v149, v149
	v_add_f32_e32 v151, 1.0, v151
	v_rcp_f32_e32 v152, v152
	v_add_f32_e32 v153, 1.0, v153
	v_rcp_f32_e32 v154, v154
	v_add_f32_e32 v155, 1.0, v155
	v_rcp_f32_e32 v151, v151
	v_rcp_f32_e32 v153, v153
	v_rcp_f32_e32 v155, v155
	v_cvt_pk_bf16_f32 v148, v148, v149
	v_cvt_pk_bf16_f32 v149, v152, v154
	v_add_co_u32_e32 v152, vcc, s6, v136
	v_cvt_pk_bf16_f32 v150, v150, v151
	v_cvt_pk_bf16_f32 v151, v153, v155
	v_addc_co_u32_e32 v153, vcc, 0, v137, vcc
	global_store_dwordx4 v[152:153], v[148:151], off
	v_fma_f32 v152, v46, v141, v134
	v_fma_f32 v154, v47, v141, v135
	v_fma_f32 v149, v40, v141, v128
	v_mul_f32_e32 v149, 0xbfb8aa3b, v149
	v_exp_f32_e32 v149, v149
	v_fma_f32 v148, v44, v141, v132
	v_mul_f32_e32 v148, 0xbfb8aa3b, v148
	v_fma_f32 v151, v41, v141, v129
	v_add_f32_e32 v149, 1.0, v149
	v_rcp_f32_e32 v150, v149
	v_fma_f32 v149, v45, v141, v133
	v_mul_f32_e32 v149, 0xbfb8aa3b, v149
	v_mul_f32_e32 v152, 0xbfb8aa3b, v152
	v_fma_f32 v153, v42, v141, v130
	v_mul_f32_e32 v154, 0xbfb8aa3b, v154
	v_fma_f32 v155, v43, v141, v131
	v_exp_f32_e32 v148, v148
	v_exp_f32_e32 v149, v149
	v_mul_f32_e32 v151, 0xbfb8aa3b, v151
	v_exp_f32_e32 v152, v152
	v_mul_f32_e32 v153, 0xbfb8aa3b, v153
	v_exp_f32_e32 v154, v154
	v_mul_f32_e32 v155, 0xbfb8aa3b, v155
	v_exp_f32_e32 v151, v151
	v_exp_f32_e32 v153, v153
	v_exp_f32_e32 v155, v155
	v_add_f32_e32 v148, 1.0, v148
	v_add_f32_e32 v149, 1.0, v149
	v_add_f32_e32 v152, 1.0, v152
	v_add_f32_e32 v154, 1.0, v154
	v_fma_f32 v128, v32, v140, v128
	v_rcp_f32_e32 v148, v148
	v_rcp_f32_e32 v149, v149
	v_add_f32_e32 v151, 1.0, v151
	v_rcp_f32_e32 v152, v152
	v_add_f32_e32 v153, 1.0, v153
	v_rcp_f32_e32 v154, v154
	v_add_f32_e32 v155, 1.0, v155
	v_mul_f32_e32 v128, 0xbfb8aa3b, v128
	v_fma_f32 v129, v33, v140, v129
	v_rcp_f32_e32 v151, v151
	v_rcp_f32_e32 v153, v153
	v_rcp_f32_e32 v155, v155
	v_exp_f32_e32 v128, v128
	v_mul_f32_e32 v129, 0xbfb8aa3b, v129
	v_fma_f32 v130, v34, v140, v130
	v_exp_f32_e32 v129, v129
	v_mul_f32_e32 v130, 0xbfb8aa3b, v130
	v_exp_f32_e32 v130, v130
	v_cvt_pk_bf16_f32 v148, v148, v149
	v_cvt_pk_bf16_f32 v149, v152, v154
	v_add_co_u32_e32 v152, vcc, s79, v136
	v_cvt_pk_bf16_f32 v150, v150, v151
	v_cvt_pk_bf16_f32 v151, v153, v155
	v_addc_co_u32_e32 v153, vcc, 0, v137, vcc
	v_add_f32_e32 v128, 1.0, v128
	global_store_dwordx4 v[152:153], v[148:151], off
	v_fma_f32 v132, v36, v140, v132
	v_add_f32_e32 v129, 1.0, v129
	v_rcp_f32_e32 v148, v128
	v_fma_f32 v128, v37, v140, v133
	v_mul_f32_e32 v132, 0xbfb8aa3b, v132
	v_mul_f32_e32 v128, 0xbfb8aa3b, v128
	v_rcp_f32_e32 v133, v129
	v_fma_f32 v129, v38, v140, v134
	v_add_f32_e32 v130, 1.0, v130
	v_fmac_f32_e32 v135, v39, v140
	v_fmac_f32_e32 v131, v35, v140
	v_exp_f32_e32 v132, v132
	v_exp_f32_e32 v128, v128
	v_mul_f32_e32 v129, 0xbfb8aa3b, v129
	v_rcp_f32_e32 v134, v130
	v_mul_f32_e32 v130, 0xbfb8aa3b, v135
	v_mul_f32_e32 v131, 0xbfb8aa3b, v131
	v_exp_f32_e32 v129, v129
	v_exp_f32_e32 v130, v130
	v_exp_f32_e32 v131, v131
	v_add_f32_e32 v132, 1.0, v132
	v_add_f32_e32 v128, 1.0, v128
	v_rcp_f32_e32 v132, v132
	v_rcp_f32_e32 v128, v128
	v_add_f32_e32 v129, 1.0, v129
	v_add_f32_e32 v130, 1.0, v130
	v_add_f32_e32 v131, 1.0, v131
	v_rcp_f32_e32 v129, v129
	v_rcp_f32_e32 v130, v130
	v_rcp_f32_e32 v131, v131
	v_cvt_pk_bf16_f32 v128, v132, v128
	v_add_co_u32_e32 v132, vcc, s87, v136
	v_cvt_pk_bf16_f32 v129, v129, v130
	v_cvt_pk_bf16_f32 v130, v148, v133
	v_cvt_pk_bf16_f32 v131, v134, v131
	v_addc_co_u32_e32 v133, vcc, 0, v137, vcc
	global_store_dwordx4 v[132:133], v[128:131], off
	s_movk_i32 s10, 0x6000
	s_waitcnt vmcnt(8)
; __device__ __forceinline__ u32x4 pack8(const f32x4& a, const f32x4& b) { u32x4 w; w.x = pk2(a[0], a[1]); w.y = pk2(a[2], a[3]); w.z = pk2(b[0], b[1]); w.w = pk2(b[2], b[3]); return w; }
; __device__ __forceinline__ float sigm(float x) { return __builtin_amdgcn_rcpf(1.0f + __builtin_amdgcn_exp2f(x * -1.4426950408889634f)); }
;     __device__ __forceinline__ void operator()(const f32x4 (&acc)[2][2][4][2], const Unit& u, int wr, int wc, int fr, int fq) const {
;     ...
;                 for (int ai = 0; ai < 2; ++ai)
; #pragma unroll
;                     for (int m = 0; m < 4; ++m) {
;                         const f32x4 a0 = acc[ai][bj][m][0] * rx[ai][m] + bv0, a1 = acc[ai][bj][m][1] * rx[ai][m] + bv1; f32x4 o0, o1;
; #pragma unroll
;                         for (int e = 0; e < 4; ++e) { o0[e] = sigm(a0[e]); o1[e] = sigm(a1[e]); }
;                         *(u32x4*)(tmpb + ((ai * 4 + m) * 2 + bj) * 8192 + voff) = pack8(o0, o1); }
	v_fma_f32 v149, v89, v147, v157
	v_mul_f32_e32 v149, 0xbfb8aa3b, v149
	v_exp_f32_e32 v149, v149
	s_waitcnt vmcnt(8)
	v_fma_f32 v138, v92, v147, v160
	v_fma_f32 v148, v93, v147, v161
	v_mul_f32_e32 v138, 0xbfb8aa3b, v138
	v_add_f32_e32 v149, 1.0, v149
	v_fma_f32 v139, v88, v147, v156
	v_mul_f32_e32 v148, 0xbfb8aa3b, v148
	v_rcp_f32_e32 v150, v149
	v_fma_f32 v149, v94, v147, v162
	v_fma_f32 v151, v90, v147, v158
	v_fma_f32 v152, v95, v147, v163
	v_fma_f32 v147, v91, v147, v159
	v_exp_f32_e32 v138, v138
	v_mul_f32_e32 v139, 0xbfb8aa3b, v139
	v_exp_f32_e32 v148, v148
	v_mul_f32_e32 v149, 0xbfb8aa3b, v149
	v_mul_f32_e32 v151, 0xbfb8aa3b, v151
	v_mul_f32_e32 v152, 0xbfb8aa3b, v152
	v_mul_f32_e32 v147, 0xbfb8aa3b, v147
	v_exp_f32_e32 v139, v139
	v_exp_f32_e32 v149, v149
	v_exp_f32_e32 v151, v151
	v_exp_f32_e32 v152, v152
	v_exp_f32_e32 v147, v147
	v_add_f32_e32 v138, 1.0, v138
	v_add_f32_e32 v148, 1.0, v148
	v_rcp_f32_e32 v138, v138
	v_add_f32_e32 v139, 1.0, v139
	v_rcp_f32_e32 v148, v148
	v_add_f32_e32 v149, 1.0, v149
	v_add_f32_e32 v151, 1.0, v151
	v_add_f32_e32 v152, 1.0, v152
	v_add_f32_e32 v147, 1.0, v147
	v_rcp_f32_e32 v139, v139
	v_rcp_f32_e32 v149, v149
	v_rcp_f32_e32 v151, v151
	v_rcp_f32_e32 v152, v152
	v_rcp_f32_e32 v147, v147
	v_cvt_pk_bf16_f32 v148, v138, v148
	v_add_co_u32_e32 v138, vcc, s82, v136
	v_cvt_pk_bf16_f32 v149, v149, v152
	v_cvt_pk_bf16_f32 v150, v139, v150
	v_cvt_pk_bf16_f32 v151, v151, v147
	v_addc_co_u32_e32 v139, vcc, 0, v137, vcc
	global_store_dwordx4 v[138:139], v[148:151], off
	v_fma_f32 v138, v84, v145, v160
	v_fma_f32 v147, v85, v145, v161
	v_fma_f32 v148, v81, v145, v157
	v_mul_f32_e32 v148, 0xbfb8aa3b, v148
	v_exp_f32_e32 v148, v148
	v_mul_f32_e32 v138, 0xbfb8aa3b, v138
	v_mul_f32_e32 v147, 0xbfb8aa3b, v147
	v_exp_f32_e32 v138, v138
	v_add_f32_e32 v148, 1.0, v148
	v_rcp_f32_e32 v150, v148
	v_fma_f32 v148, v86, v145, v162
	v_mul_f32_e32 v148, 0xbfb8aa3b, v148
	v_exp_f32_e32 v148, v148
	v_exp_f32_e32 v147, v147
	v_fma_f32 v139, v80, v145, v156
	v_add_f32_e32 v138, 1.0, v138
	v_add_f32_e32 v148, 1.0, v148
	v_rcp_f32_e32 v149, v148
	v_fma_f32 v148, v82, v145, v158
	v_mul_f32_e32 v148, 0xbfb8aa3b, v148
	v_exp_f32_e32 v148, v148
	v_mul_f32_e32 v139, 0xbfb8aa3b, v139
	v_add_f32_e32 v147, 1.0, v147
	v_rcp_f32_e32 v138, v138
	v_add_f32_e32 v148, 1.0, v148
	v_rcp_f32_e32 v151, v148
	v_fma_f32 v148, v87, v145, v163
	v_mul_f32_e32 v148, 0xbfb8aa3b, v148
	v_fma_f32 v145, v83, v145, v159
	v_exp_f32_e32 v148, v148
	v_mul_f32_e32 v145, 0xbfb8aa3b, v145
	v_exp_f32_e32 v139, v139
	v_rcp_f32_e32 v147, v147
	v_exp_f32_e32 v145, v145
	v_add_f32_e32 v148, 1.0, v148
	v_add_f32_e32 v139, 1.0, v139
	v_rcp_f32_e32 v152, v148
	v_add_f32_e32 v145, 1.0, v145
	v_cvt_pk_bf16_f32 v148, v138, v147
	v_fma_f32 v147, v73, v146, v157
	v_rcp_f32_e32 v139, v139
	v_rcp_f32_e32 v145, v145
	v_mul_f32_e32 v147, 0xbfb8aa3b, v147
	v_exp_f32_e32 v147, v147
	v_add_co_u32_e32 v138, vcc, s10, v136
	v_cvt_pk_bf16_f32 v149, v149, v152
	v_cvt_pk_bf16_f32 v150, v139, v150
	v_cvt_pk_bf16_f32 v151, v151, v145
	v_addc_co_u32_e32 v139, vcc, 0, v137, vcc
	global_store_dwordx4 v[138:139], v[148:151], off
	v_fma_f32 v138, v76, v146, v160
	v_fma_f32 v145, v77, v146, v161
	v_add_f32_e32 v147, 1.0, v147
	v_mul_f32_e32 v138, 0xbfb8aa3b, v138
	v_fma_f32 v139, v72, v146, v156
	v_mul_f32_e32 v145, 0xbfb8aa3b, v145
	v_rcp_f32_e32 v148, v147
	v_fma_f32 v147, v78, v146, v162
	v_fma_f32 v149, v74, v146, v158
	v_fma_f32 v150, v79, v146, v163
	v_fma_f32 v146, v75, v146, v159
	v_exp_f32_e32 v138, v138
	v_mul_f32_e32 v139, 0xbfb8aa3b, v139
	v_exp_f32_e32 v145, v145
	v_mul_f32_e32 v147, 0xbfb8aa3b, v147
	v_mul_f32_e32 v149, 0xbfb8aa3b, v149
	v_mul_f32_e32 v150, 0xbfb8aa3b, v150
	v_mul_f32_e32 v146, 0xbfb8aa3b, v146
	v_exp_f32_e32 v139, v139
	v_exp_f32_e32 v147, v147
	v_exp_f32_e32 v149, v149
	v_exp_f32_e32 v150, v150
	v_exp_f32_e32 v146, v146
	v_add_f32_e32 v138, 1.0, v138
	v_add_f32_e32 v145, 1.0, v145
	v_rcp_f32_e32 v138, v138
	v_add_f32_e32 v139, 1.0, v139
	v_rcp_f32_e32 v145, v145
	v_add_f32_e32 v147, 1.0, v147
	v_add_f32_e32 v149, 1.0, v149
	v_add_f32_e32 v150, 1.0, v150
	v_add_f32_e32 v146, 1.0, v146
	v_rcp_f32_e32 v139, v139
	v_rcp_f32_e32 v147, v147
	v_rcp_f32_e32 v149, v149
	v_rcp_f32_e32 v150, v150
	v_rcp_f32_e32 v151, v146
	s_mov_b32 s10, 0xa000
	v_cvt_pk_bf16_f32 v146, v138, v145
	v_add_co_u32_e32 v138, vcc, s10, v136
	v_cvt_pk_bf16_f32 v147, v147, v150
	v_cvt_pk_bf16_f32 v148, v139, v148
	v_cvt_pk_bf16_f32 v149, v149, v151
	v_addc_co_u32_e32 v139, vcc, 0, v137, vcc
	global_store_dwordx4 v[138:139], v[146:149], off
	v_fma_f32 v138, v68, v143, v160
	v_fma_f32 v145, v69, v143, v161
	v_fma_f32 v146, v65, v143, v157
	v_mul_f32_e32 v146, 0xbfb8aa3b, v146
	v_exp_f32_e32 v146, v146
	v_mul_f32_e32 v138, 0xbfb8aa3b, v138
	v_mul_f32_e32 v145, 0xbfb8aa3b, v145
	v_exp_f32_e32 v138, v138
	v_add_f32_e32 v146, 1.0, v146
	v_rcp_f32_e32 v148, v146
	v_fma_f32 v146, v70, v143, v162
	v_mul_f32_e32 v146, 0xbfb8aa3b, v146
	v_exp_f32_e32 v146, v146
	v_exp_f32_e32 v145, v145
	v_fma_f32 v139, v64, v143, v156
	v_add_f32_e32 v138, 1.0, v138
	v_add_f32_e32 v146, 1.0, v146
	v_rcp_f32_e32 v147, v146
	v_fma_f32 v146, v66, v143, v158
	v_mul_f32_e32 v146, 0xbfb8aa3b, v146
	v_exp_f32_e32 v146, v146
	v_mul_f32_e32 v139, 0xbfb8aa3b, v139
	v_add_f32_e32 v145, 1.0, v145
	v_rcp_f32_e32 v138, v138
	v_add_f32_e32 v146, 1.0, v146
	v_rcp_f32_e32 v149, v146
	v_fma_f32 v146, v71, v143, v163
	v_mul_f32_e32 v146, 0xbfb8aa3b, v146
	v_fma_f32 v143, v67, v143, v159
	v_exp_f32_e32 v146, v146
	v_mul_f32_e32 v143, 0xbfb8aa3b, v143
	v_exp_f32_e32 v139, v139
	v_rcp_f32_e32 v145, v145
	v_exp_f32_e32 v143, v143
; __device__ __forceinline__ u32x4 pack8(const f32x4& a, const f32x4& b) { u32x4 w; w.x = pk2(a[0], a[1]); w.y = pk2(a[2], a[3]); w.z = pk2(b[0], b[1]); w.w = pk2(b[2], b[3]); return w; }
; __device__ __forceinline__ float sigm(float x) { return __builtin_amdgcn_rcpf(1.0f + __builtin_amdgcn_exp2f(x * -1.4426950408889634f)); }
;     __device__ __forceinline__ void operator()(const f32x4 (&acc)[2][2][4][2], const Unit& u, int wr, int wc, int fr, int fq) const {
;     ...
;                 for (int ai = 0; ai < 2; ++ai)
; #pragma unroll
;                     for (int m = 0; m < 4; ++m) {
;                         const f32x4 a0 = acc[ai][bj][m][0] * rx[ai][m] + bv0, a1 = acc[ai][bj][m][1] * rx[ai][m] + bv1; f32x4 o0, o1;
; #pragma unroll
;                         for (int e = 0; e < 4; ++e) { o0[e] = sigm(a0[e]); o1[e] = sigm(a1[e]); }
;                         *(u32x4*)(tmpb + ((ai * 4 + m) * 2 + bj) * 8192 + voff) = pack8(o0, o1); }
	v_add_f32_e32 v146, 1.0, v146
	v_add_f32_e32 v139, 1.0, v139
	v_rcp_f32_e32 v150, v146
	v_add_f32_e32 v143, 1.0, v143
	v_cvt_pk_bf16_f32 v146, v138, v145
	v_fma_f32 v145, v25, v144, v157
	v_rcp_f32_e32 v139, v139
	v_rcp_f32_e32 v143, v143
	v_mul_f32_e32 v145, 0xbfb8aa3b, v145
	v_exp_f32_e32 v145, v145
	v_add_co_u32_e32 v138, vcc, s98, v136
	v_cvt_pk_bf16_f32 v147, v147, v150
	v_cvt_pk_bf16_f32 v148, v139, v148
	v_cvt_pk_bf16_f32 v149, v149, v143
	v_addc_co_u32_e32 v139, vcc, 0, v137, vcc
	global_store_dwordx4 v[138:139], v[146:149], off
	v_fma_f32 v138, v28, v144, v160
	v_fma_f32 v143, v29, v144, v161
	v_add_f32_e32 v145, 1.0, v145
	v_mul_f32_e32 v138, 0xbfb8aa3b, v138
	v_fma_f32 v139, v24, v144, v156
	v_mul_f32_e32 v143, 0xbfb8aa3b, v143
	v_rcp_f32_e32 v146, v145
	v_fma_f32 v145, v30, v144, v162
	v_fma_f32 v147, v26, v144, v158
	v_fma_f32 v148, v31, v144, v163
	v_fma_f32 v144, v27, v144, v159
	v_exp_f32_e32 v138, v138
	v_mul_f32_e32 v139, 0xbfb8aa3b, v139
	v_exp_f32_e32 v143, v143
	v_mul_f32_e32 v145, 0xbfb8aa3b, v145
	v_mul_f32_e32 v147, 0xbfb8aa3b, v147
	v_mul_f32_e32 v148, 0xbfb8aa3b, v148
	v_mul_f32_e32 v144, 0xbfb8aa3b, v144
	v_exp_f32_e32 v139, v139
	v_exp_f32_e32 v145, v145
	v_exp_f32_e32 v147, v147
	v_exp_f32_e32 v148, v148
	v_exp_f32_e32 v144, v144
	v_add_f32_e32 v138, 1.0, v138
	v_add_f32_e32 v143, 1.0, v143
	v_rcp_f32_e32 v138, v138
	v_add_f32_e32 v139, 1.0, v139
	v_rcp_f32_e32 v143, v143
	v_add_f32_e32 v145, 1.0, v145
	v_add_f32_e32 v147, 1.0, v147
	v_add_f32_e32 v148, 1.0, v148
	v_add_f32_e32 v144, 1.0, v144
	v_rcp_f32_e32 v139, v139
	v_rcp_f32_e32 v145, v145
	v_rcp_f32_e32 v147, v147
	v_rcp_f32_e32 v148, v148
	v_rcp_f32_e32 v149, v144
	v_cvt_pk_bf16_f32 v144, v138, v143
	v_add_co_u32_e32 v138, vcc, s5, v136
	v_cvt_pk_bf16_f32 v145, v145, v148
	v_cvt_pk_bf16_f32 v146, v139, v146
	v_cvt_pk_bf16_f32 v147, v147, v149
	v_addc_co_u32_e32 v139, vcc, 0, v137, vcc
	global_store_dwordx4 v[138:139], v[144:147], off
	v_fma_f32 v138, v20, v142, v160
	v_fma_f32 v143, v21, v142, v161
	v_mul_f32_e32 v138, 0xbfb8aa3b, v138
	v_fma_f32 v139, v16, v142, v156
	v_mul_f32_e32 v143, 0xbfb8aa3b, v143
	v_fma_f32 v144, v17, v142, v157
	v_fma_f32 v145, v22, v142, v162
	v_fma_f32 v146, v18, v142, v158
	v_fma_f32 v147, v23, v142, v163
	v_fma_f32 v142, v19, v142, v159
	v_exp_f32_e32 v138, v138
	v_mul_f32_e32 v139, 0xbfb8aa3b, v139
	v_exp_f32_e32 v143, v143
	v_mul_f32_e32 v144, 0xbfb8aa3b, v144
	v_mul_f32_e32 v145, 0xbfb8aa3b, v145
	v_mul_f32_e32 v146, 0xbfb8aa3b, v146
	v_mul_f32_e32 v147, 0xbfb8aa3b, v147
	v_mul_f32_e32 v142, 0xbfb8aa3b, v142
	v_exp_f32_e32 v139, v139
	v_exp_f32_e32 v144, v144
	v_exp_f32_e32 v145, v145
	v_exp_f32_e32 v146, v146
	v_exp_f32_e32 v147, v147
	v_exp_f32_e32 v142, v142
	v_add_f32_e32 v138, 1.0, v138
	v_add_f32_e32 v143, 1.0, v143
	v_rcp_f32_e32 v138, v138
	v_add_f32_e32 v139, 1.0, v139
	v_rcp_f32_e32 v143, v143
	v_add_f32_e32 v144, 1.0, v144
	v_add_f32_e32 v145, 1.0, v145
	v_add_f32_e32 v146, 1.0, v146
	v_add_f32_e32 v147, 1.0, v147
	v_add_f32_e32 v142, 1.0, v142
	v_rcp_f32_e32 v139, v139
	v_rcp_f32_e32 v144, v144
	v_rcp_f32_e32 v145, v145
	v_rcp_f32_e32 v146, v146
	v_rcp_f32_e32 v147, v147
	v_rcp_f32_e32 v148, v142
	v_cvt_pk_bf16_f32 v142, v138, v143
	v_add_co_u32_e32 v138, vcc, s7, v136
	v_cvt_pk_bf16_f32 v143, v145, v147
	v_cvt_pk_bf16_f32 v144, v139, v144
	v_cvt_pk_bf16_f32 v145, v146, v148
	v_addc_co_u32_e32 v139, vcc, 0, v137, vcc
	global_store_dwordx4 v[138:139], v[142:145], off
	v_fma_f32 v138, v12, v141, v160
	v_mul_f32_e32 v138, 0xbfb8aa3b, v138
	v_fma_f32 v143, v9, v141, v157
	v_mul_f32_e32 v143, 0xbfb8aa3b, v143
	v_exp_f32_e32 v143, v143
	v_fma_f32 v142, v13, v141, v161
	v_fma_f32 v139, v8, v141, v156
	v_mul_f32_e32 v142, 0xbfb8aa3b, v142
	v_add_f32_e32 v143, 1.0, v143
	v_rcp_f32_e32 v144, v143
	v_fma_f32 v143, v14, v141, v162
	v_fma_f32 v145, v10, v141, v158
	v_fma_f32 v146, v15, v141, v163
	v_fma_f32 v141, v11, v141, v159
	v_exp_f32_e32 v138, v138
	v_mul_f32_e32 v139, 0xbfb8aa3b, v139
	v_exp_f32_e32 v142, v142
	v_mul_f32_e32 v143, 0xbfb8aa3b, v143
	v_mul_f32_e32 v145, 0xbfb8aa3b, v145
	v_mul_f32_e32 v146, 0xbfb8aa3b, v146
	v_mul_f32_e32 v141, 0xbfb8aa3b, v141
	v_exp_f32_e32 v139, v139
	v_exp_f32_e32 v143, v143
	v_exp_f32_e32 v145, v145
	v_exp_f32_e32 v146, v146
	v_exp_f32_e32 v141, v141
	v_add_f32_e32 v138, 1.0, v138
	v_add_f32_e32 v142, 1.0, v142
	v_fma_f32 v128, v0, v140, v156
	v_rcp_f32_e32 v138, v138
	v_add_f32_e32 v139, 1.0, v139
	v_rcp_f32_e32 v142, v142
	v_add_f32_e32 v143, 1.0, v143
	v_add_f32_e32 v145, 1.0, v145
	v_add_f32_e32 v146, 1.0, v146
	v_add_f32_e32 v141, 1.0, v141
	v_mul_f32_e32 v128, 0xbfb8aa3b, v128
	v_fma_f32 v129, v1, v140, v157
	v_rcp_f32_e32 v139, v139
	v_rcp_f32_e32 v143, v143
	v_rcp_f32_e32 v145, v145
	v_rcp_f32_e32 v146, v146
	v_rcp_f32_e32 v141, v141
	v_exp_f32_e32 v128, v128
	v_mul_f32_e32 v129, 0xbfb8aa3b, v129
	v_fma_f32 v130, v2, v140, v158
	v_exp_f32_e32 v129, v129
	v_mul_f32_e32 v130, 0xbfb8aa3b, v130
	v_exp_f32_e32 v130, v130
	v_cvt_pk_bf16_f32 v142, v138, v142
	v_add_co_u32_e32 v138, vcc, s85, v136
	v_cvt_pk_bf16_f32 v143, v143, v146
	v_cvt_pk_bf16_f32 v144, v139, v144
	v_cvt_pk_bf16_f32 v145, v145, v141
	v_addc_co_u32_e32 v139, vcc, 0, v137, vcc
	v_add_f32_e32 v128, 1.0, v128
	global_store_dwordx4 v[138:139], v[142:145], off
	v_fma_f32 v132, v4, v140, v160
	v_rcp_f32_e32 v138, v128
	v_fma_f32 v128, v5, v140, v161
	v_add_f32_e32 v129, 1.0, v129
	v_mul_f32_e32 v132, 0xbfb8aa3b, v132
	v_mul_f32_e32 v128, 0xbfb8aa3b, v128
	v_rcp_f32_e32 v133, v129
	v_fma_f32 v129, v6, v140, v162
	v_add_f32_e32 v130, 1.0, v130
	v_fma_f32 v135, v7, v140, v163
	v_fma_f32 v131, v3, v140, v159
	v_exp_f32_e32 v132, v132
	v_exp_f32_e32 v128, v128
	v_mul_f32_e32 v129, 0xbfb8aa3b, v129
	v_rcp_f32_e32 v134, v130
	v_mul_f32_e32 v130, 0xbfb8aa3b, v135
	v_mul_f32_e32 v131, 0xbfb8aa3b, v131
	v_exp_f32_e32 v129, v129
	v_exp_f32_e32 v130, v130
	v_exp_f32_e32 v131, v131
	v_add_f32_e32 v132, 1.0, v132
	v_add_f32_e32 v128, 1.0, v128
	v_rcp_f32_e32 v132, v132
	v_rcp_f32_e32 v128, v128
	v_add_f32_e32 v129, 1.0, v129
	v_add_f32_e32 v130, 1.0, v130
	v_add_f32_e32 v131, 1.0, v131
	v_rcp_f32_e32 v129, v129
	v_rcp_f32_e32 v130, v130
	v_rcp_f32_e32 v131, v131
	v_cvt_pk_bf16_f32 v128, v132, v128
	v_add_co_u32_e32 v132, vcc, 0x1e000, v136
	v_cvt_pk_bf16_f32 v129, v129, v130
	v_cvt_pk_bf16_f32 v130, v138, v133
	v_cvt_pk_bf16_f32 v131, v134, v131
	v_addc_co_u32_e32 v133, vcc, 0, v137, vcc
	global_store_dwordx4 v[132:133], v[128:131], off
